# K-loops without any s_setprio (on top of trims and implied-wait removal)
# baseline (speedup 1.0000x reference)
; #define PG8_STAGE(bufoff, gbase, voff) do { _Pragma("unroll") for (int _i = 0; _i < 2; ++_i) \
;         __builtin_amdgcn_global_load_lds((const unsigned*)((const char*)(gbase) + (voff)[_i]), (LAS unsigned*)(lds + (bufoff) + ldsw + _i * 8192), 16, 0, 0); } while (0)
; #define PG8_LDA(dst, b, h) do { _Pragma("unroll") for (int m = 0; m < 4; ++m) _Pragma("unroll") for (int k = 0; k < 2; ++k) dst[m][k] = *(const LAS bf16x8*)(lds + PG8_SA(b, h) + aoff + m * 2048 + k * 1024); } while (0)
; #define PG8_LDB(dst, b, h) do { _Pragma("unroll") for (int n = 0; n < 2; ++n) _Pragma("unroll") for (int k = 0; k < 2; ++k) dst[n][k] = *(const LAS bf16x8*)(lds + PG8_SB(b, h) + boff + n * 2048 + k * 1024); } while (0)
; #define PG8_WAIT_V(n) asm volatile("s_waitcnt vmcnt(" #n ")" ::: "memory")
; template <class Epi, int AMODE>
; __device__ __forceinline__ void gemm_phase(LAS unsigned char* lds, const Gemm g, const StaticOrder& S, const Epi& E, int stagger_us, int tid_in) {
;     ...
;         for (int t = 0; t < nt; t += 2) {
;             const bool last = (t == nt - 2);
;             const char* a1 = cA + (size_t)(t + 1) * kstep;
;             const char* a2 = last ? nA : cA + (size_t)(t + 2) * kstep; const char* b2 = last ? nB : cB + (size_t)(t + 2) * kstep;
;             const char* a3 = a2 + kstep; const char* b3 = b2 + kstep;
;             PG8_LDB(B0, 0, 0); PG8_LDB(B1, 0, 1); PG8_SCHED; PG8_LDA(At, 0, 0); PG8_STAGE(PG8_SA(1, 1), a1 + hstepA, voffA);
;             PG8_WAIT_V(8); PG8_WAIT_L(0); PG8_BAR; PG8_MMA(0, 0, At, B0); PG8_MMA(0, 1, At, B1); PG8_BAR; PG8_SCHED;
;             PG8_LDA(At, 0, 1); PG8_STAGE(PG8_SB(0, 0), b2, voffB); PG8_STAGE(PG8_SB(0, 1), b2 + hstepB, voffB); PG8_STAGE(PG8_SA(0, 0), a2, voffA);
;             PG8_WAIT_V(8); PG8_WAIT_L(0); PG8_BAR; PG8_MMA(1, 0, At, B0); PG8_MMA(1, 1, At, B1); PG8_BAR; PG8_SCHED;
;             PG8_LDB(B0, 1, 0); PG8_LDB(B1, 1, 1); PG8_SCHED; PG8_LDA(At, 1, 0); PG8_STAGE(PG8_SA(0, 1), a2 + hstepA, voffA);
;             PG8_WAIT_V(8); PG8_WAIT_L(0); PG8_BAR; PG8_MMA(0, 0, At, B0); PG8_MMA(0, 1, At, B1); PG8_BAR; PG8_SCHED;
;             PG8_LDA(At, 1, 1); PG8_STAGE(PG8_SB(1, 0), b3, voffB); PG8_STAGE(PG8_SB(1, 1), b3 + hstepB, voffB); PG8_STAGE(PG8_SA(1, 0), a3, voffA);
;             PG8_WAIT_V(8); PG8_WAIT_L(0); PG8_BAR; PG8_MMA(1, 0, At, B0); PG8_MMA(1, 1, At, B1); PG8_BAR; PG8_SCHED;
.LBB0_396:
	s_add_u32 s4, s60, 0xfff80080
	s_addc_u32 s5, s61, -1
	s_add_i32 s30, 0, 0x10000
	s_cmp_eq_u32 s29, 28
	s_cselect_b32 s7, s27, s5
	s_cselect_b32 s6, s28, s4
	v_add_u32_e32 v140, s30, v162
	s_cselect_b32 s5, s49, vcc_hi
	s_cselect_b32 s4, s51, vcc_lo
	s_add_i32 s44, 0, 0x14000
	ds_read_b128 v[144:147], v140
	ds_read_b128 v[148:151], v140 offset:1024
	ds_read_b128 v[152:155], v140 offset:2048
	ds_read_b128 v[156:159], v140 offset:3072
	v_add_u32_e32 v140, s44, v162
	ds_read_b128 v[166:169], v140
	ds_read_b128 v[170:173], v140 offset:1024
	ds_read_b128 v[174:177], v140 offset:2048
	ds_read_b128 v[178:181], v140 offset:3072
	v_lshl_add_u64 v[140:141], s[60:61], 0, v[136:137]
	s_add_i32 m0, s57, 0xc000
	ds_read_b128 v[182:185], v164
	ds_read_b128 v[186:189], v164 offset:1024
	ds_read_b128 v[190:193], v164 offset:2048
	ds_read_b128 v[194:197], v164 offset:3072
	ds_read_b128 v[198:201], v164 offset:4096
	ds_read_b128 v[202:205], v164 offset:5120
	ds_read_b128 v[206:209], v164 offset:6144
	ds_read_b128 v[210:213], v164 offset:7168
	global_load_lds_dwordx4 v[140:141], off
	s_add_i32 m0, s57, 0xe000
	v_lshl_add_u64 v[140:141], s[60:61], 0, v[138:139]
	global_load_lds_dwordx4 v[140:141], off
	s_waitcnt vmcnt(8) lgkmcnt(0)
	s_barrier
	v_mfma_f32_16x16x32_bf16 v[126:129], v[144:147], v[182:185], v[126:129]
	v_mfma_f32_16x16x32_bf16 v[122:125], v[152:155], v[182:185], v[122:125]
	v_mfma_f32_16x16x32_bf16 v[110:113], v[144:147], v[190:193], v[110:113]
	v_mfma_f32_16x16x32_bf16 v[106:109], v[152:155], v[190:193], v[106:109]
	v_mfma_f32_16x16x32_bf16 v[94:97], v[144:147], v[198:201], v[94:97]
	v_mfma_f32_16x16x32_bf16 v[90:93], v[152:155], v[198:201], v[90:93]
	v_mfma_f32_16x16x32_bf16 v[78:81], v[144:147], v[206:209], v[78:81]
	v_mfma_f32_16x16x32_bf16 v[74:77], v[152:155], v[206:209], v[74:77]
	v_mfma_f32_16x16x32_bf16 v[126:129], v[148:151], v[186:189], v[126:129]
	v_mfma_f32_16x16x32_bf16 v[122:125], v[156:159], v[186:189], v[122:125]
	v_mfma_f32_16x16x32_bf16 v[110:113], v[148:151], v[194:197], v[110:113]
	v_mfma_f32_16x16x32_bf16 v[106:109], v[156:159], v[194:197], v[106:109]
	v_mfma_f32_16x16x32_bf16 v[94:97], v[148:151], v[202:205], v[94:97]
	v_mfma_f32_16x16x32_bf16 v[90:93], v[156:159], v[202:205], v[90:93]
	v_mfma_f32_16x16x32_bf16 v[78:81], v[148:151], v[210:213], v[78:81]
	v_mfma_f32_16x16x32_bf16 v[74:77], v[156:159], v[210:213], v[74:77]
	v_mfma_f32_16x16x32_bf16 v[118:121], v[166:169], v[182:185], v[118:121]
	v_mfma_f32_16x16x32_bf16 v[114:117], v[174:177], v[182:185], v[114:117]
	v_mfma_f32_16x16x32_bf16 v[102:105], v[166:169], v[190:193], v[102:105]
	v_mfma_f32_16x16x32_bf16 v[98:101], v[174:177], v[190:193], v[98:101]
	v_mfma_f32_16x16x32_bf16 v[86:89], v[166:169], v[198:201], v[86:89]
	v_mfma_f32_16x16x32_bf16 v[82:85], v[174:177], v[198:201], v[82:85]
	v_mfma_f32_16x16x32_bf16 v[70:73], v[166:169], v[206:209], v[70:73]
	v_mfma_f32_16x16x32_bf16 v[66:69], v[174:177], v[206:209], v[66:69]
	v_mfma_f32_16x16x32_bf16 v[118:121], v[170:173], v[186:189], v[118:121]
	v_mfma_f32_16x16x32_bf16 v[114:117], v[178:181], v[186:189], v[114:117]
	v_mfma_f32_16x16x32_bf16 v[102:105], v[170:173], v[194:197], v[102:105]
	v_mfma_f32_16x16x32_bf16 v[98:101], v[178:181], v[194:197], v[98:101]
	v_mfma_f32_16x16x32_bf16 v[86:89], v[170:173], v[202:205], v[86:89]
	v_mfma_f32_16x16x32_bf16 v[82:85], v[178:181], v[202:205], v[82:85]
	v_mfma_f32_16x16x32_bf16 v[70:73], v[170:173], v[210:213], v[70:73]
	v_mfma_f32_16x16x32_bf16 v[66:69], v[178:181], v[210:213], v[66:69]
	s_barrier
	s_add_i32 s30, s30, s66
	v_lshl_add_u64 v[140:141], s[4:5], 0, v[0:1]
	s_mov_b32 m0, s30
	ds_read_b128 v[182:185], v164 offset:16384
	ds_read_b128 v[186:189], v164 offset:17408
	ds_read_b128 v[190:193], v164 offset:18432
	ds_read_b128 v[194:197], v164 offset:19456
	ds_read_b128 v[198:201], v164 offset:20480
	ds_read_b128 v[202:205], v164 offset:21504
	ds_read_b128 v[206:209], v164 offset:22528
	ds_read_b128 v[210:213], v164 offset:23552
	global_load_lds_dwordx4 v[140:141], off
	s_add_i32 m0, s30, 0x2000
	s_add_u32 s30, s4, 0x80000
	v_lshl_add_u64 v[160:161], s[4:5], 0, v[130:131]
	s_addc_u32 s31, s5, 0
	s_add_i32 s44, s44, s66
	global_load_lds_dwordx4 v[160:161], off
	v_lshl_add_u64 v[214:215], s[30:31], 0, v[0:1]
	s_mov_b32 m0, s44
	v_lshl_add_u64 v[216:217], s[6:7], 0, v[132:133]
	global_load_lds_dwordx4 v[214:215], off
	s_add_i32 m0, s44, 0x2000
	v_lshl_add_u64 v[214:215], s[30:31], 0, v[130:131]
	global_load_lds_dwordx4 v[214:215], off
	s_mov_b32 m0, s57
	v_lshl_add_u64 v[214:215], s[6:7], 0, v[134:135]
	global_load_lds_dwordx4 v[214:215], off
	s_mov_b32 m0, s59
	s_nop 0
	global_load_lds_dwordx4 v[216:217], off
	s_waitcnt vmcnt(8) lgkmcnt(0)
	s_barrier
; #define PG8_STAGE(bufoff, gbase, voff) do { _Pragma("unroll") for (int _i = 0; _i < 2; ++_i) \
;         __builtin_amdgcn_global_load_lds((const unsigned*)((const char*)(gbase) + (voff)[_i]), (LAS unsigned*)(lds + (bufoff) + ldsw + _i * 8192), 16, 0, 0); } while (0)
; #define PG8_LDA(dst, b, h) do { _Pragma("unroll") for (int m = 0; m < 4; ++m) _Pragma("unroll") for (int k = 0; k < 2; ++k) dst[m][k] = *(const LAS bf16x8*)(lds + PG8_SA(b, h) + aoff + m * 2048 + k * 1024); } while (0)
; #define PG8_LDB(dst, b, h) do { _Pragma("unroll") for (int n = 0; n < 2; ++n) _Pragma("unroll") for (int k = 0; k < 2; ++k) dst[n][k] = *(const LAS bf16x8*)(lds + PG8_SB(b, h) + boff + n * 2048 + k * 1024); } while (0)
; #define PG8_WAIT_V(n) asm volatile("s_waitcnt vmcnt(" #n ")" ::: "memory")
; template <class Epi, int AMODE>
; __device__ __forceinline__ void gemm_phase(LAS unsigned char* lds, const Gemm g, const StaticOrder& S, const Epi& E, int stagger_us, int tid_in) {
;     ...
;         for (int t = 0; t < nt; t += 2) {
;             const bool last = (t == nt - 2);
;             const char* a1 = cA + (size_t)(t + 1) * kstep;
;             const char* a2 = last ? nA : cA + (size_t)(t + 2) * kstep; const char* b2 = last ? nB : cB + (size_t)(t + 2) * kstep;
;             const char* a3 = a2 + kstep; const char* b3 = b2 + kstep;
;             PG8_LDB(B0, 0, 0); PG8_LDB(B1, 0, 1); PG8_SCHED; PG8_LDA(At, 0, 0); PG8_STAGE(PG8_SA(1, 1), a1 + hstepA, voffA);
;             PG8_WAIT_V(8); PG8_WAIT_L(0); PG8_BAR; PG8_MMA(0, 0, At, B0); PG8_MMA(0, 1, At, B1); PG8_BAR; PG8_SCHED;
;             PG8_LDA(At, 0, 1); PG8_STAGE(PG8_SB(0, 0), b2, voffB); PG8_STAGE(PG8_SB(0, 1), b2 + hstepB, voffB); PG8_STAGE(PG8_SA(0, 0), a2, voffA);
;             PG8_WAIT_V(8); PG8_WAIT_L(0); PG8_BAR; PG8_MMA(1, 0, At, B0); PG8_MMA(1, 1, At, B1); PG8_BAR; PG8_SCHED;
;             PG8_LDB(B0, 1, 0); PG8_LDB(B1, 1, 1); PG8_SCHED; PG8_LDA(At, 1, 0); PG8_STAGE(PG8_SA(0, 1), a2 + hstepA, voffA);
;             PG8_WAIT_V(8); PG8_WAIT_L(0); PG8_BAR; PG8_MMA(0, 0, At, B0); PG8_MMA(0, 1, At, B1); PG8_BAR; PG8_SCHED;
;             PG8_LDA(At, 1, 1); PG8_STAGE(PG8_SB(1, 0), b3, voffB); PG8_STAGE(PG8_SB(1, 1), b3 + hstepB, voffB); PG8_STAGE(PG8_SA(1, 0), a3, voffA);
;             PG8_WAIT_V(8); PG8_WAIT_L(0); PG8_BAR; PG8_MMA(1, 0, At, B0); PG8_MMA(1, 1, At, B1); PG8_BAR; PG8_SCHED;
	v_mfma_f32_16x16x32_bf16 v[62:65], v[144:147], v[182:185], v[62:65]
	v_mfma_f32_16x16x32_bf16 v[58:61], v[152:155], v[182:185], v[58:61]
	v_mfma_f32_16x16x32_bf16 v[46:49], v[144:147], v[190:193], v[46:49]
	v_mfma_f32_16x16x32_bf16 v[42:45], v[152:155], v[190:193], v[42:45]
	v_mfma_f32_16x16x32_bf16 v[30:33], v[144:147], v[198:201], v[30:33]
	v_mfma_f32_16x16x32_bf16 v[26:29], v[152:155], v[198:201], v[26:29]
	v_mfma_f32_16x16x32_bf16 v[14:17], v[144:147], v[206:209], v[14:17]
	v_mfma_f32_16x16x32_bf16 v[10:13], v[152:155], v[206:209], v[10:13]
	v_mfma_f32_16x16x32_bf16 v[62:65], v[148:151], v[186:189], v[62:65]
	v_mfma_f32_16x16x32_bf16 v[58:61], v[156:159], v[186:189], v[58:61]
	v_mfma_f32_16x16x32_bf16 v[46:49], v[148:151], v[194:197], v[46:49]
	v_mfma_f32_16x16x32_bf16 v[42:45], v[156:159], v[194:197], v[42:45]
	v_mfma_f32_16x16x32_bf16 v[30:33], v[148:151], v[202:205], v[30:33]
	v_mfma_f32_16x16x32_bf16 v[26:29], v[156:159], v[202:205], v[26:29]
	v_mfma_f32_16x16x32_bf16 v[14:17], v[148:151], v[210:213], v[14:17]
	v_mfma_f32_16x16x32_bf16 v[10:13], v[156:159], v[210:213], v[10:13]
	v_mfma_f32_16x16x32_bf16 v[54:57], v[166:169], v[182:185], v[54:57]
	v_mfma_f32_16x16x32_bf16 v[50:53], v[174:177], v[182:185], v[50:53]
	v_mfma_f32_16x16x32_bf16 v[38:41], v[166:169], v[190:193], v[38:41]
	v_mfma_f32_16x16x32_bf16 v[34:37], v[174:177], v[190:193], v[34:37]
	v_mfma_f32_16x16x32_bf16 v[22:25], v[166:169], v[198:201], v[22:25]
	v_mfma_f32_16x16x32_bf16 v[18:21], v[174:177], v[198:201], v[18:21]
	v_mfma_f32_16x16x32_bf16 v[6:9], v[166:169], v[206:209], v[6:9]
	v_mfma_f32_16x16x32_bf16 v[2:5], v[174:177], v[206:209], v[2:5]
	v_mfma_f32_16x16x32_bf16 v[54:57], v[170:173], v[186:189], v[54:57]
	v_mfma_f32_16x16x32_bf16 v[50:53], v[178:181], v[186:189], v[50:53]
	v_mfma_f32_16x16x32_bf16 v[38:41], v[170:173], v[194:197], v[38:41]
	v_mfma_f32_16x16x32_bf16 v[34:37], v[178:181], v[194:197], v[34:37]
	v_mfma_f32_16x16x32_bf16 v[22:25], v[170:173], v[202:205], v[22:25]
	v_mfma_f32_16x16x32_bf16 v[18:21], v[178:181], v[202:205], v[18:21]
	v_mfma_f32_16x16x32_bf16 v[6:9], v[170:173], v[210:213], v[6:9]
	v_mfma_f32_16x16x32_bf16 v[2:5], v[178:181], v[210:213], v[2:5]
	s_barrier
	s_add_i32 s30, 0, 0x18000
	v_add_u32_e32 v142, s30, v162
	s_add_i32 s31, 0, 0x1c000
	ds_read_b128 v[144:147], v142
	ds_read_b128 v[148:151], v142 offset:1024
	ds_read_b128 v[152:155], v142 offset:2048
	ds_read_b128 v[156:159], v142 offset:3072
	v_add_u32_e32 v142, s31, v162
	ds_read_b128 v[166:169], v142
	ds_read_b128 v[170:173], v142 offset:1024
	ds_read_b128 v[174:177], v142 offset:2048
	ds_read_b128 v[178:181], v142 offset:3072
	s_add_u32 s6, s6, 0x80000
	s_addc_u32 s7, s7, 0
	s_mov_b32 m0, s87
	v_lshl_add_u64 v[218:219], s[6:7], 0, v[134:135]
	ds_read_b128 v[182:185], v164 offset:32768
	ds_read_b128 v[186:189], v164 offset:33792
	ds_read_b128 v[190:193], v164 offset:34816
	ds_read_b128 v[194:197], v164 offset:35840
	ds_read_b128 v[198:201], v164 offset:36864
	ds_read_b128 v[202:205], v164 offset:37888
	ds_read_b128 v[206:209], v164 offset:38912
	ds_read_b128 v[210:213], v164 offset:39936
	global_load_lds_dwordx4 v[218:219], off
	s_mov_b32 m0, s91
	v_lshl_add_u64 v[218:219], s[6:7], 0, v[132:133]
	global_load_lds_dwordx4 v[218:219], off
	s_waitcnt vmcnt(8) lgkmcnt(0)
	s_barrier
	v_mfma_f32_16x16x32_bf16 v[126:129], v[144:147], v[182:185], v[126:129]
	v_mfma_f32_16x16x32_bf16 v[122:125], v[152:155], v[182:185], v[122:125]
	v_mfma_f32_16x16x32_bf16 v[110:113], v[144:147], v[190:193], v[110:113]
	v_mfma_f32_16x16x32_bf16 v[106:109], v[152:155], v[190:193], v[106:109]
	v_mfma_f32_16x16x32_bf16 v[94:97], v[144:147], v[198:201], v[94:97]
	v_mfma_f32_16x16x32_bf16 v[90:93], v[152:155], v[198:201], v[90:93]
	v_mfma_f32_16x16x32_bf16 v[78:81], v[144:147], v[206:209], v[78:81]
	v_mfma_f32_16x16x32_bf16 v[74:77], v[152:155], v[206:209], v[74:77]
	v_mfma_f32_16x16x32_bf16 v[126:129], v[148:151], v[186:189], v[126:129]
	v_mfma_f32_16x16x32_bf16 v[122:125], v[156:159], v[186:189], v[122:125]
	v_mfma_f32_16x16x32_bf16 v[110:113], v[148:151], v[194:197], v[110:113]
	v_mfma_f32_16x16x32_bf16 v[106:109], v[156:159], v[194:197], v[106:109]
	v_mfma_f32_16x16x32_bf16 v[94:97], v[148:151], v[202:205], v[94:97]
	v_mfma_f32_16x16x32_bf16 v[90:93], v[156:159], v[202:205], v[90:93]
	v_mfma_f32_16x16x32_bf16 v[78:81], v[148:151], v[210:213], v[78:81]
	v_mfma_f32_16x16x32_bf16 v[74:77], v[156:159], v[210:213], v[74:77]
	v_mfma_f32_16x16x32_bf16 v[118:121], v[166:169], v[182:185], v[118:121]
	v_mfma_f32_16x16x32_bf16 v[114:117], v[174:177], v[182:185], v[114:117]
	v_mfma_f32_16x16x32_bf16 v[102:105], v[166:169], v[190:193], v[102:105]
	v_mfma_f32_16x16x32_bf16 v[98:101], v[174:177], v[190:193], v[98:101]
	v_mfma_f32_16x16x32_bf16 v[86:89], v[166:169], v[198:201], v[86:89]
	v_mfma_f32_16x16x32_bf16 v[82:85], v[174:177], v[198:201], v[82:85]
	v_mfma_f32_16x16x32_bf16 v[70:73], v[166:169], v[206:209], v[70:73]
	v_mfma_f32_16x16x32_bf16 v[66:69], v[174:177], v[206:209], v[66:69]
	v_mfma_f32_16x16x32_bf16 v[118:121], v[170:173], v[186:189], v[118:121]
	v_mfma_f32_16x16x32_bf16 v[114:117], v[178:181], v[186:189], v[114:117]
	v_mfma_f32_16x16x32_bf16 v[102:105], v[170:173], v[194:197], v[102:105]
	v_mfma_f32_16x16x32_bf16 v[98:101], v[178:181], v[194:197], v[98:101]
	v_mfma_f32_16x16x32_bf16 v[86:89], v[170:173], v[202:205], v[86:89]
	v_mfma_f32_16x16x32_bf16 v[82:85], v[178:181], v[202:205], v[82:85]
	v_mfma_f32_16x16x32_bf16 v[70:73], v[170:173], v[210:213], v[70:73]
	v_mfma_f32_16x16x32_bf16 v[66:69], v[178:181], v[210:213], v[66:69]
	s_barrier
; #define PG8_STAGE(bufoff, gbase, voff) do { _Pragma("unroll") for (int _i = 0; _i < 2; ++_i) \
;         __builtin_amdgcn_global_load_lds((const unsigned*)((const char*)(gbase) + (voff)[_i]), (LAS unsigned*)(lds + (bufoff) + ldsw + _i * 8192), 16, 0, 0); } while (0)
; #define PG8_LDA(dst, b, h) do { _Pragma("unroll") for (int m = 0; m < 4; ++m) _Pragma("unroll") for (int k = 0; k < 2; ++k) dst[m][k] = *(const LAS bf16x8*)(lds + PG8_SA(b, h) + aoff + m * 2048 + k * 1024); } while (0)
; #define PG8_LDB(dst, b, h) do { _Pragma("unroll") for (int n = 0; n < 2; ++n) _Pragma("unroll") for (int k = 0; k < 2; ++k) dst[n][k] = *(const LAS bf16x8*)(lds + PG8_SB(b, h) + boff + n * 2048 + k * 1024); } while (0)
; #define PG8_BAR __builtin_amdgcn_s_barrier()
; template <class Epi, int AMODE>
; __device__ __forceinline__ void gemm_phase(LAS unsigned char* lds, const Gemm g, const StaticOrder& S, const Epi& E, int stagger_us, int tid_in) {
;     ...
;         for (int t = 0; t < nt; t += 2) {
;             const bool last = (t == nt - 2);
;             const char* a1 = cA + (size_t)(t + 1) * kstep;
;             const char* a2 = last ? nA : cA + (size_t)(t + 2) * kstep; const char* b2 = last ? nB : cB + (size_t)(t + 2) * kstep;
;             const char* a3 = a2 + kstep; const char* b3 = b2 + kstep;
;             PG8_LDB(B0, 0, 0); PG8_LDB(B1, 0, 1); PG8_SCHED; PG8_LDA(At, 0, 0); PG8_STAGE(PG8_SA(1, 1), a1 + hstepA, voffA);
;             PG8_WAIT_V(8); PG8_WAIT_L(0); PG8_BAR; PG8_MMA(0, 0, At, B0); PG8_MMA(0, 1, At, B1); PG8_BAR; PG8_SCHED;
;             PG8_LDA(At, 0, 1); PG8_STAGE(PG8_SB(0, 0), b2, voffB); PG8_STAGE(PG8_SB(0, 1), b2 + hstepB, voffB); PG8_STAGE(PG8_SA(0, 0), a2, voffA);
;             PG8_WAIT_V(8); PG8_WAIT_L(0); PG8_BAR; PG8_MMA(1, 0, At, B0); PG8_MMA(1, 1, At, B1); PG8_BAR; PG8_SCHED;
;             PG8_LDB(B0, 1, 0); PG8_LDB(B1, 1, 1); PG8_SCHED; PG8_LDA(At, 1, 0); PG8_STAGE(PG8_SA(0, 1), a2 + hstepA, voffA);
;             PG8_WAIT_V(8); PG8_WAIT_L(0); PG8_BAR; PG8_MMA(0, 0, At, B0); PG8_MMA(0, 1, At, B1); PG8_BAR; PG8_SCHED;
;             PG8_LDA(At, 1, 1); PG8_STAGE(PG8_SB(1, 0), b3, voffB); PG8_STAGE(PG8_SB(1, 1), b3 + hstepB, voffB); PG8_STAGE(PG8_SA(1, 0), a3, voffA);
;             PG8_WAIT_V(8); PG8_WAIT_L(0); PG8_BAR; PG8_MMA(1, 0, At, B0); PG8_MMA(1, 1, At, B1); PG8_BAR; PG8_SCHED;
;         }
;         if (wr == 0) PG8_BAR;
	s_add_i32 s6, s30, s66
	v_lshl_add_u64 v[140:141], v[140:141], 0, s[74:75]
	s_mov_b32 m0, s6
	ds_read_b128 v[182:185], v164 offset:49152
	ds_read_b128 v[186:189], v164 offset:50176
	ds_read_b128 v[190:193], v164 offset:51200
	ds_read_b128 v[194:197], v164 offset:52224
	ds_read_b128 v[198:201], v164 offset:53248
	ds_read_b128 v[202:205], v164 offset:54272
	ds_read_b128 v[206:209], v164 offset:55296
	ds_read_b128 v[210:213], v164 offset:56320
	global_load_lds_dwordx4 v[140:141], off
	s_add_i32 m0, s6, 0x2000
	s_add_u32 s4, s4, 0x80080
	v_lshl_add_u64 v[140:141], v[160:161], 0, s[74:75]
	s_addc_u32 s5, s5, 0
	s_add_i32 s6, s31, s66
	global_load_lds_dwordx4 v[140:141], off
	s_mov_b32 m0, s6
	v_lshl_add_u64 v[140:141], s[4:5], 0, v[0:1]
	global_load_lds_dwordx4 v[140:141], off
	s_add_i32 m0, s6, 0x2000
	v_lshl_add_u64 v[140:141], s[4:5], 0, v[130:131]
	global_load_lds_dwordx4 v[140:141], off
	s_mov_b32 m0, s95
	v_lshl_add_u64 v[140:141], v[214:215], 0, s[74:75]
	global_load_lds_dwordx4 v[140:141], off
	s_mov_b32 m0, s96
	v_lshl_add_u64 v[140:141], v[216:217], 0, s[74:75]
	global_load_lds_dwordx4 v[140:141], off
	s_waitcnt vmcnt(8) lgkmcnt(0)
	s_barrier
	v_mfma_f32_16x16x32_bf16 v[62:65], v[144:147], v[182:185], v[62:65]
	v_mfma_f32_16x16x32_bf16 v[58:61], v[152:155], v[182:185], v[58:61]
	v_mfma_f32_16x16x32_bf16 v[46:49], v[144:147], v[190:193], v[46:49]
	v_mfma_f32_16x16x32_bf16 v[42:45], v[152:155], v[190:193], v[42:45]
	v_mfma_f32_16x16x32_bf16 v[30:33], v[144:147], v[198:201], v[30:33]
	v_mfma_f32_16x16x32_bf16 v[26:29], v[152:155], v[198:201], v[26:29]
	v_mfma_f32_16x16x32_bf16 v[14:17], v[144:147], v[206:209], v[14:17]
	v_mfma_f32_16x16x32_bf16 v[10:13], v[152:155], v[206:209], v[10:13]
	v_mfma_f32_16x16x32_bf16 v[62:65], v[148:151], v[186:189], v[62:65]
	v_mfma_f32_16x16x32_bf16 v[58:61], v[156:159], v[186:189], v[58:61]
	v_mfma_f32_16x16x32_bf16 v[46:49], v[148:151], v[194:197], v[46:49]
	v_mfma_f32_16x16x32_bf16 v[42:45], v[156:159], v[194:197], v[42:45]
	v_mfma_f32_16x16x32_bf16 v[30:33], v[148:151], v[202:205], v[30:33]
	v_mfma_f32_16x16x32_bf16 v[26:29], v[156:159], v[202:205], v[26:29]
	v_mfma_f32_16x16x32_bf16 v[14:17], v[148:151], v[210:213], v[14:17]
	v_mfma_f32_16x16x32_bf16 v[10:13], v[156:159], v[210:213], v[10:13]
	v_mfma_f32_16x16x32_bf16 v[54:57], v[166:169], v[182:185], v[54:57]
	v_mfma_f32_16x16x32_bf16 v[50:53], v[174:177], v[182:185], v[50:53]
	v_mfma_f32_16x16x32_bf16 v[38:41], v[166:169], v[190:193], v[38:41]
	v_mfma_f32_16x16x32_bf16 v[34:37], v[174:177], v[190:193], v[34:37]
	v_mfma_f32_16x16x32_bf16 v[22:25], v[166:169], v[198:201], v[22:25]
	v_mfma_f32_16x16x32_bf16 v[18:21], v[174:177], v[198:201], v[18:21]
	v_mfma_f32_16x16x32_bf16 v[6:9], v[166:169], v[206:209], v[6:9]
	v_mfma_f32_16x16x32_bf16 v[2:5], v[174:177], v[206:209], v[2:5]
	v_mfma_f32_16x16x32_bf16 v[54:57], v[170:173], v[186:189], v[54:57]
	v_mfma_f32_16x16x32_bf16 v[50:53], v[178:181], v[186:189], v[50:53]
	v_mfma_f32_16x16x32_bf16 v[38:41], v[170:173], v[194:197], v[38:41]
	v_mfma_f32_16x16x32_bf16 v[34:37], v[178:181], v[194:197], v[34:37]
	v_mfma_f32_16x16x32_bf16 v[22:25], v[170:173], v[202:205], v[22:25]
	v_mfma_f32_16x16x32_bf16 v[18:21], v[178:181], v[202:205], v[18:21]
	v_mfma_f32_16x16x32_bf16 v[6:9], v[170:173], v[210:213], v[6:9]
	v_mfma_f32_16x16x32_bf16 v[2:5], v[178:181], v[210:213], v[2:5]
	s_barrier
	s_add_i32 s29, s29, 2
	s_add_u32 s60, s60, 0x100
	s_addc_u32 s61, s61, 0
	s_add_u32 vcc_lo, vcc_lo, 0x100
	s_addc_u32 vcc_hi, vcc_hi, 0
	s_cmp_gt_u32 s29, 29
	s_cbranch_scc0 .LBB0_396
	s_and_b64 vcc, exec, s[46:47]
	s_cbranch_vccz .LBB0_399
	s_barrier

; #define PG8_STAGE(bufoff, gbase, voff) do { _Pragma("unroll") for (int _i = 0; _i < 2; ++_i) \
;         __builtin_amdgcn_global_load_lds((const unsigned*)((const char*)(gbase) + (voff)[_i]), (LAS unsigned*)(lds + (bufoff) + ldsw + _i * 8192), 16, 0, 0); } while (0)
; #define PG8_LDA(dst, b, h) do { _Pragma("unroll") for (int m = 0; m < 4; ++m) _Pragma("unroll") for (int k = 0; k < 2; ++k) dst[m][k] = *(const LAS bf16x8*)(lds + PG8_SA(b, h) + aoff + m * 2048 + k * 1024); } while (0)
; #define PG8_LDB(dst, b, h) do { _Pragma("unroll") for (int n = 0; n < 2; ++n) _Pragma("unroll") for (int k = 0; k < 2; ++k) dst[n][k] = *(const LAS bf16x8*)(lds + PG8_SB(b, h) + boff + n * 2048 + k * 1024); } while (0)
; #define PG8_WAIT_V(n) asm volatile("s_waitcnt vmcnt(" #n ")" ::: "memory")
; template <class Epi, int AMODE>
; __device__ __forceinline__ void gemm_phase(LAS unsigned char* lds, const Gemm g, const StaticOrder& S, const Epi& E, int stagger_us, int tid_in) {
;     ...
;         for (int t = 0; t < nt; t += 2) {
;             const bool last = (t == nt - 2);
;             const char* a1 = cA + (size_t)(t + 1) * kstep;
;             const char* a2 = last ? nA : cA + (size_t)(t + 2) * kstep; const char* b2 = last ? nB : cB + (size_t)(t + 2) * kstep;
;             const char* a3 = a2 + kstep; const char* b3 = b2 + kstep;
;             PG8_LDB(B0, 0, 0); PG8_LDB(B1, 0, 1); PG8_SCHED; PG8_LDA(At, 0, 0); PG8_STAGE(PG8_SA(1, 1), a1 + hstepA, voffA);
;             PG8_WAIT_V(8); PG8_WAIT_L(0); PG8_BAR; PG8_MMA(0, 0, At, B0); PG8_MMA(0, 1, At, B1); PG8_BAR; PG8_SCHED;
;             PG8_LDA(At, 0, 1); PG8_STAGE(PG8_SB(0, 0), b2, voffB); PG8_STAGE(PG8_SB(0, 1), b2 + hstepB, voffB); PG8_STAGE(PG8_SA(0, 0), a2, voffA);
;             PG8_WAIT_V(8); PG8_WAIT_L(0); PG8_BAR; PG8_MMA(1, 0, At, B0); PG8_MMA(1, 1, At, B1); PG8_BAR; PG8_SCHED;
;             PG8_LDB(B0, 1, 0); PG8_LDB(B1, 1, 1); PG8_SCHED; PG8_LDA(At, 1, 0); PG8_STAGE(PG8_SA(0, 1), a2 + hstepA, voffA);
;             PG8_WAIT_V(8); PG8_WAIT_L(0); PG8_BAR; PG8_MMA(0, 0, At, B0); PG8_MMA(0, 1, At, B1); PG8_BAR; PG8_SCHED;
;             PG8_LDA(At, 1, 1); PG8_STAGE(PG8_SB(1, 0), b3, voffB); PG8_STAGE(PG8_SB(1, 1), b3 + hstepB, voffB); PG8_STAGE(PG8_SA(1, 0), a3, voffA);
;             PG8_WAIT_V(8); PG8_WAIT_L(0); PG8_BAR; PG8_MMA(1, 0, At, B0); PG8_MMA(1, 1, At, B1); PG8_BAR; PG8_SCHED;
.LBB0_1199:
	s_add_u32 s4, s46, 0x100
	s_addc_u32 s5, s47, 0
	s_add_i32 s34, 0, 0x10000
	s_cmp_eq_u32 s31, 28
	s_cselect_b32 s95, s61, s5
	s_cselect_b32 s94, vcc_lo, s4
	s_cselect_b32 s7, s59, s30
	s_cselect_b32 s6, vcc_hi, s29
	s_add_i32 s35, 0, 0x14000
	v_add_u32_e32 v62, s34, v205
	v_add_u32_e32 v158, s35, v205
	ds_read_b128 v[50:53], v62
	ds_read_b128 v[54:57], v62 offset:1024
	ds_read_b128 v[58:61], v62 offset:2048
	ds_read_b128 v[62:65], v62 offset:3072
	ds_read_b128 v[146:149], v158
	ds_read_b128 v[150:153], v158 offset:1024
	ds_read_b128 v[154:157], v158 offset:2048
	ds_read_b128 v[158:161], v158 offset:3072
	v_lshl_add_u64 v[200:201], s[46:47], 0, v[176:177]
	s_add_i32 m0, s66, 0xc000
	ds_read_b128 v[162:165], v207
	ds_read_b128 v[166:169], v207 offset:1024
	ds_read_b128 v[170:173], v207 offset:2048
	ds_read_b128 v[180:183], v207 offset:3072
	ds_read_b128 v[184:187], v207 offset:4096
	ds_read_b128 v[188:191], v207 offset:5120
	ds_read_b128 v[192:195], v207 offset:6144
	ds_read_b128 v[196:199], v207 offset:7168
	global_load_lds_dwordx4 v[200:201], off
	s_add_i32 m0, s66, 0xe000
	v_lshl_add_u64 v[200:201], s[46:47], 0, v[178:179]
	global_load_lds_dwordx4 v[200:201], off
	s_waitcnt vmcnt(8) lgkmcnt(0)
	s_barrier
	v_mfma_f32_16x16x32_bf16 v[142:145], v[50:53], v[162:165], v[142:145]
	v_mfma_f32_16x16x32_bf16 v[138:141], v[58:61], v[162:165], v[138:141]
	v_mfma_f32_16x16x32_bf16 v[126:129], v[50:53], v[170:173], v[126:129]
	v_mfma_f32_16x16x32_bf16 v[122:125], v[58:61], v[170:173], v[122:125]
	v_mfma_f32_16x16x32_bf16 v[110:113], v[50:53], v[184:187], v[110:113]
	v_mfma_f32_16x16x32_bf16 v[106:109], v[58:61], v[184:187], v[106:109]
	v_mfma_f32_16x16x32_bf16 v[94:97], v[50:53], v[192:195], v[94:97]
	v_mfma_f32_16x16x32_bf16 v[90:93], v[58:61], v[192:195], v[90:93]
	v_mfma_f32_16x16x32_bf16 v[142:145], v[54:57], v[166:169], v[142:145]
	v_mfma_f32_16x16x32_bf16 v[138:141], v[62:65], v[166:169], v[138:141]
	v_mfma_f32_16x16x32_bf16 v[126:129], v[54:57], v[180:183], v[126:129]
	v_mfma_f32_16x16x32_bf16 v[122:125], v[62:65], v[180:183], v[122:125]
	v_mfma_f32_16x16x32_bf16 v[110:113], v[54:57], v[188:191], v[110:113]
	v_mfma_f32_16x16x32_bf16 v[106:109], v[62:65], v[188:191], v[106:109]
	v_mfma_f32_16x16x32_bf16 v[94:97], v[54:57], v[196:199], v[94:97]
	v_mfma_f32_16x16x32_bf16 v[90:93], v[62:65], v[196:199], v[90:93]
	v_mfma_f32_16x16x32_bf16 v[134:137], v[146:149], v[162:165], v[134:137]
	v_mfma_f32_16x16x32_bf16 v[130:133], v[154:157], v[162:165], v[130:133]
	v_mfma_f32_16x16x32_bf16 v[118:121], v[146:149], v[170:173], v[118:121]
	v_mfma_f32_16x16x32_bf16 v[114:117], v[154:157], v[170:173], v[114:117]
	v_mfma_f32_16x16x32_bf16 v[102:105], v[146:149], v[184:187], v[102:105]
	v_mfma_f32_16x16x32_bf16 v[98:101], v[154:157], v[184:187], v[98:101]
	v_mfma_f32_16x16x32_bf16 v[86:89], v[146:149], v[192:195], v[86:89]
	v_mfma_f32_16x16x32_bf16 v[82:85], v[154:157], v[192:195], v[82:85]
	v_mfma_f32_16x16x32_bf16 v[134:137], v[150:153], v[166:169], v[134:137]
	v_mfma_f32_16x16x32_bf16 v[130:133], v[158:161], v[166:169], v[130:133]
	v_mfma_f32_16x16x32_bf16 v[118:121], v[150:153], v[180:183], v[118:121]
	v_mfma_f32_16x16x32_bf16 v[114:117], v[158:161], v[180:183], v[114:117]
	v_mfma_f32_16x16x32_bf16 v[102:105], v[150:153], v[188:191], v[102:105]
	v_mfma_f32_16x16x32_bf16 v[98:101], v[158:161], v[188:191], v[98:101]
	v_mfma_f32_16x16x32_bf16 v[86:89], v[150:153], v[196:199], v[86:89]
	v_mfma_f32_16x16x32_bf16 v[82:85], v[158:161], v[196:199], v[82:85]
	s_barrier
	s_add_i32 s34, s34, s13
	v_lshl_add_u64 v[200:201], s[6:7], 0, v[0:1]
	s_mov_b32 m0, s34
	ds_read_b128 v[162:165], v207 offset:16384
	ds_read_b128 v[166:169], v207 offset:17408
	ds_read_b128 v[170:173], v207 offset:18432
	ds_read_b128 v[180:183], v207 offset:19456
	ds_read_b128 v[184:187], v207 offset:20480
	ds_read_b128 v[188:191], v207 offset:21504
	ds_read_b128 v[192:195], v207 offset:22528
	ds_read_b128 v[196:199], v207 offset:23552
	global_load_lds_dwordx4 v[200:201], off
	s_add_i32 m0, s34, 0x2000
	s_add_u32 s46, s6, 0x80000
	v_lshl_add_u64 v[202:203], s[6:7], 0, v[174:175]
	s_addc_u32 s47, s7, 0
	s_add_i32 s34, s35, s13
	global_load_lds_dwordx4 v[202:203], off
	v_lshl_add_u64 v[208:209], s[46:47], 0, v[0:1]
	s_mov_b32 m0, s34
	v_lshl_add_u64 v[210:211], s[94:95], 0, v[174:175]
	global_load_lds_dwordx4 v[208:209], off
	s_add_i32 m0, s34, 0x2000
	v_lshl_add_u64 v[208:209], s[46:47], 0, v[174:175]
	global_load_lds_dwordx4 v[208:209], off
	s_mov_b32 m0, s66
	v_lshl_add_u64 v[208:209], s[94:95], 0, v[0:1]
	global_load_lds_dwordx4 v[208:209], off
	s_mov_b32 m0, s67
	s_nop 0
	global_load_lds_dwordx4 v[210:211], off
	s_waitcnt vmcnt(8) lgkmcnt(0)
	s_barrier
; #define PG8_STAGE(bufoff, gbase, voff) do { _Pragma("unroll") for (int _i = 0; _i < 2; ++_i) \
;         __builtin_amdgcn_global_load_lds((const unsigned*)((const char*)(gbase) + (voff)[_i]), (LAS unsigned*)(lds + (bufoff) + ldsw + _i * 8192), 16, 0, 0); } while (0)
; #define PG8_LDA(dst, b, h) do { _Pragma("unroll") for (int m = 0; m < 4; ++m) _Pragma("unroll") for (int k = 0; k < 2; ++k) dst[m][k] = *(const LAS bf16x8*)(lds + PG8_SA(b, h) + aoff + m * 2048 + k * 1024); } while (0)
; #define PG8_LDB(dst, b, h) do { _Pragma("unroll") for (int n = 0; n < 2; ++n) _Pragma("unroll") for (int k = 0; k < 2; ++k) dst[n][k] = *(const LAS bf16x8*)(lds + PG8_SB(b, h) + boff + n * 2048 + k * 1024); } while (0)
; #define PG8_WAIT_V(n) asm volatile("s_waitcnt vmcnt(" #n ")" ::: "memory")
; template <class Epi, int AMODE>
; __device__ __forceinline__ void gemm_phase(LAS unsigned char* lds, const Gemm g, const StaticOrder& S, const Epi& E, int stagger_us, int tid_in) {
;     ...
;         for (int t = 0; t < nt; t += 2) {
;             const bool last = (t == nt - 2);
;             const char* a1 = cA + (size_t)(t + 1) * kstep;
;             const char* a2 = last ? nA : cA + (size_t)(t + 2) * kstep; const char* b2 = last ? nB : cB + (size_t)(t + 2) * kstep;
;             const char* a3 = a2 + kstep; const char* b3 = b2 + kstep;
;             PG8_LDB(B0, 0, 0); PG8_LDB(B1, 0, 1); PG8_SCHED; PG8_LDA(At, 0, 0); PG8_STAGE(PG8_SA(1, 1), a1 + hstepA, voffA);
;             PG8_WAIT_V(8); PG8_WAIT_L(0); PG8_BAR; PG8_MMA(0, 0, At, B0); PG8_MMA(0, 1, At, B1); PG8_BAR; PG8_SCHED;
;             PG8_LDA(At, 0, 1); PG8_STAGE(PG8_SB(0, 0), b2, voffB); PG8_STAGE(PG8_SB(0, 1), b2 + hstepB, voffB); PG8_STAGE(PG8_SA(0, 0), a2, voffA);
;             PG8_WAIT_V(8); PG8_WAIT_L(0); PG8_BAR; PG8_MMA(1, 0, At, B0); PG8_MMA(1, 1, At, B1); PG8_BAR; PG8_SCHED;
;             PG8_LDB(B0, 1, 0); PG8_LDB(B1, 1, 1); PG8_SCHED; PG8_LDA(At, 1, 0); PG8_STAGE(PG8_SA(0, 1), a2 + hstepA, voffA);
;             PG8_WAIT_V(8); PG8_WAIT_L(0); PG8_BAR; PG8_MMA(0, 0, At, B0); PG8_MMA(0, 1, At, B1); PG8_BAR; PG8_SCHED;
;             PG8_LDA(At, 1, 1); PG8_STAGE(PG8_SB(1, 0), b3, voffB); PG8_STAGE(PG8_SB(1, 1), b3 + hstepB, voffB); PG8_STAGE(PG8_SA(1, 0), a3, voffA);
;             PG8_WAIT_V(8); PG8_WAIT_L(0); PG8_BAR; PG8_MMA(1, 0, At, B0); PG8_MMA(1, 1, At, B1); PG8_BAR; PG8_SCHED;
	v_mfma_f32_16x16x32_bf16 v[78:81], v[50:53], v[162:165], v[78:81]
	v_mfma_f32_16x16x32_bf16 v[74:77], v[58:61], v[162:165], v[74:77]
	v_mfma_f32_16x16x32_bf16 v[46:49], v[50:53], v[170:173], v[46:49]
	v_mfma_f32_16x16x32_bf16 v[42:45], v[58:61], v[170:173], v[42:45]
	v_mfma_f32_16x16x32_bf16 v[30:33], v[50:53], v[184:187], v[30:33]
	v_mfma_f32_16x16x32_bf16 v[26:29], v[58:61], v[184:187], v[26:29]
	v_mfma_f32_16x16x32_bf16 v[14:17], v[50:53], v[192:195], v[14:17]
	v_mfma_f32_16x16x32_bf16 v[10:13], v[58:61], v[192:195], v[10:13]
	v_mfma_f32_16x16x32_bf16 v[78:81], v[54:57], v[166:169], v[78:81]
	v_mfma_f32_16x16x32_bf16 v[74:77], v[62:65], v[166:169], v[74:77]
	v_mfma_f32_16x16x32_bf16 v[46:49], v[54:57], v[180:183], v[46:49]
	v_mfma_f32_16x16x32_bf16 v[42:45], v[62:65], v[180:183], v[42:45]
	v_mfma_f32_16x16x32_bf16 v[30:33], v[54:57], v[188:191], v[30:33]
	v_mfma_f32_16x16x32_bf16 v[26:29], v[62:65], v[188:191], v[26:29]
	v_mfma_f32_16x16x32_bf16 v[14:17], v[54:57], v[196:199], v[14:17]
	v_mfma_f32_16x16x32_bf16 v[10:13], v[62:65], v[196:199], v[10:13]
	v_mfma_f32_16x16x32_bf16 v[38:41], v[146:149], v[170:173], v[38:41]
	v_mfma_f32_16x16x32_bf16 v[34:37], v[154:157], v[170:173], v[34:37]
	v_mfma_f32_16x16x32_bf16 v[22:25], v[146:149], v[184:187], v[22:25]
	v_mfma_f32_16x16x32_bf16 v[18:21], v[154:157], v[184:187], v[18:21]
	v_mfma_f32_16x16x32_bf16 v[6:9], v[146:149], v[192:195], v[6:9]
	v_mfma_f32_16x16x32_bf16 v[2:5], v[154:157], v[192:195], v[2:5]
	v_mfma_f32_16x16x32_bf16 v[50:53], v[146:149], v[162:165], v[70:73]
	v_mfma_f32_16x16x32_bf16 v[54:57], v[154:157], v[162:165], v[66:69]
	v_mfma_f32_16x16x32_bf16 v[38:41], v[150:153], v[180:183], v[38:41]
	v_mfma_f32_16x16x32_bf16 v[34:37], v[158:161], v[180:183], v[34:37]
	v_mfma_f32_16x16x32_bf16 v[22:25], v[150:153], v[188:191], v[22:25]
	v_mfma_f32_16x16x32_bf16 v[18:21], v[158:161], v[188:191], v[18:21]
	v_mfma_f32_16x16x32_bf16 v[6:9], v[150:153], v[196:199], v[6:9]
	v_mfma_f32_16x16x32_bf16 v[2:5], v[158:161], v[196:199], v[2:5]
	v_mfma_f32_16x16x32_bf16 v[50:53], v[150:153], v[166:169], v[50:53]
	v_mfma_f32_16x16x32_bf16 v[54:57], v[158:161], v[166:169], v[54:57]
	s_barrier
	s_add_i32 s34, 0, 0x18000
	s_add_i32 s35, 0, 0x1c000
	v_add_u32_e32 v70, s34, v205
	v_add_u32_e32 v158, s35, v205
	ds_read_b128 v[58:61], v70
	ds_read_b128 v[62:65], v70 offset:1024
	ds_read_b128 v[66:69], v70 offset:2048
	ds_read_b128 v[70:73], v70 offset:3072
	ds_read_b128 v[146:149], v158
	ds_read_b128 v[150:153], v158 offset:1024
	ds_read_b128 v[154:157], v158 offset:2048
	ds_read_b128 v[158:161], v158 offset:3072
	s_add_u32 s46, s94, 0x80000
	s_addc_u32 s47, s95, 0
	s_mov_b32 m0, s69
	v_lshl_add_u64 v[212:213], s[46:47], 0, v[0:1]
	ds_read_b128 v[162:165], v207 offset:32768
	ds_read_b128 v[166:169], v207 offset:33792
	ds_read_b128 v[170:173], v207 offset:34816
	ds_read_b128 v[180:183], v207 offset:35840
	ds_read_b128 v[184:187], v207 offset:36864
	ds_read_b128 v[188:191], v207 offset:37888
	ds_read_b128 v[192:195], v207 offset:38912
	ds_read_b128 v[196:199], v207 offset:39936
	global_load_lds_dwordx4 v[212:213], off
	s_mov_b32 m0, s72
	v_lshl_add_u64 v[212:213], s[46:47], 0, v[174:175]
	global_load_lds_dwordx4 v[212:213], off
	s_waitcnt vmcnt(8) lgkmcnt(0)
	s_barrier
	v_mfma_f32_16x16x32_bf16 v[142:145], v[58:61], v[162:165], v[142:145]
	v_mfma_f32_16x16x32_bf16 v[138:141], v[66:69], v[162:165], v[138:141]
	v_mfma_f32_16x16x32_bf16 v[126:129], v[58:61], v[170:173], v[126:129]
	v_mfma_f32_16x16x32_bf16 v[122:125], v[66:69], v[170:173], v[122:125]
	v_mfma_f32_16x16x32_bf16 v[110:113], v[58:61], v[184:187], v[110:113]
	v_mfma_f32_16x16x32_bf16 v[106:109], v[66:69], v[184:187], v[106:109]
	v_mfma_f32_16x16x32_bf16 v[94:97], v[58:61], v[192:195], v[94:97]
	v_mfma_f32_16x16x32_bf16 v[90:93], v[66:69], v[192:195], v[90:93]
	v_mfma_f32_16x16x32_bf16 v[142:145], v[62:65], v[166:169], v[142:145]
	v_mfma_f32_16x16x32_bf16 v[138:141], v[70:73], v[166:169], v[138:141]
	v_mfma_f32_16x16x32_bf16 v[126:129], v[62:65], v[180:183], v[126:129]
	v_mfma_f32_16x16x32_bf16 v[122:125], v[70:73], v[180:183], v[122:125]
	v_mfma_f32_16x16x32_bf16 v[110:113], v[62:65], v[188:191], v[110:113]
	v_mfma_f32_16x16x32_bf16 v[106:109], v[70:73], v[188:191], v[106:109]
	v_mfma_f32_16x16x32_bf16 v[94:97], v[62:65], v[196:199], v[94:97]
	v_mfma_f32_16x16x32_bf16 v[90:93], v[70:73], v[196:199], v[90:93]
	v_mfma_f32_16x16x32_bf16 v[134:137], v[146:149], v[162:165], v[134:137]
	v_mfma_f32_16x16x32_bf16 v[130:133], v[154:157], v[162:165], v[130:133]
	v_mfma_f32_16x16x32_bf16 v[118:121], v[146:149], v[170:173], v[118:121]
	v_mfma_f32_16x16x32_bf16 v[114:117], v[154:157], v[170:173], v[114:117]
	v_mfma_f32_16x16x32_bf16 v[102:105], v[146:149], v[184:187], v[102:105]
	v_mfma_f32_16x16x32_bf16 v[98:101], v[154:157], v[184:187], v[98:101]
	v_mfma_f32_16x16x32_bf16 v[86:89], v[146:149], v[192:195], v[86:89]
	v_mfma_f32_16x16x32_bf16 v[82:85], v[154:157], v[192:195], v[82:85]
	v_mfma_f32_16x16x32_bf16 v[134:137], v[150:153], v[166:169], v[134:137]
	v_mfma_f32_16x16x32_bf16 v[130:133], v[158:161], v[166:169], v[130:133]
	v_mfma_f32_16x16x32_bf16 v[118:121], v[150:153], v[180:183], v[118:121]
	v_mfma_f32_16x16x32_bf16 v[114:117], v[158:161], v[180:183], v[114:117]
	v_mfma_f32_16x16x32_bf16 v[102:105], v[150:153], v[188:191], v[102:105]
	v_mfma_f32_16x16x32_bf16 v[98:101], v[158:161], v[188:191], v[98:101]
	v_mfma_f32_16x16x32_bf16 v[86:89], v[150:153], v[196:199], v[86:89]
	v_mfma_f32_16x16x32_bf16 v[82:85], v[158:161], v[196:199], v[82:85]
	s_barrier
; #define PG8_STAGE(bufoff, gbase, voff) do { _Pragma("unroll") for (int _i = 0; _i < 2; ++_i) \
;         __builtin_amdgcn_global_load_lds((const unsigned*)((const char*)(gbase) + (voff)[_i]), (LAS unsigned*)(lds + (bufoff) + ldsw + _i * 8192), 16, 0, 0); } while (0)
; #define PG8_LDA(dst, b, h) do { _Pragma("unroll") for (int m = 0; m < 4; ++m) _Pragma("unroll") for (int k = 0; k < 2; ++k) dst[m][k] = *(const LAS bf16x8*)(lds + PG8_SA(b, h) + aoff + m * 2048 + k * 1024); } while (0)
; #define PG8_LDB(dst, b, h) do { _Pragma("unroll") for (int n = 0; n < 2; ++n) _Pragma("unroll") for (int k = 0; k < 2; ++k) dst[n][k] = *(const LAS bf16x8*)(lds + PG8_SB(b, h) + boff + n * 2048 + k * 1024); } while (0)
; #define PG8_BAR __builtin_amdgcn_s_barrier()
; template <class Epi, int AMODE>
; __device__ __forceinline__ void gemm_phase(LAS unsigned char* lds, const Gemm g, const StaticOrder& S, const Epi& E, int stagger_us, int tid_in) {
;     ...
;         for (int t = 0; t < nt; t += 2) {
;             const bool last = (t == nt - 2);
;             const char* a1 = cA + (size_t)(t + 1) * kstep;
;             const char* a2 = last ? nA : cA + (size_t)(t + 2) * kstep; const char* b2 = last ? nB : cB + (size_t)(t + 2) * kstep;
;             const char* a3 = a2 + kstep; const char* b3 = b2 + kstep;
;             PG8_LDB(B0, 0, 0); PG8_LDB(B1, 0, 1); PG8_SCHED; PG8_LDA(At, 0, 0); PG8_STAGE(PG8_SA(1, 1), a1 + hstepA, voffA);
;             PG8_WAIT_V(8); PG8_WAIT_L(0); PG8_BAR; PG8_MMA(0, 0, At, B0); PG8_MMA(0, 1, At, B1); PG8_BAR; PG8_SCHED;
;             PG8_LDA(At, 0, 1); PG8_STAGE(PG8_SB(0, 0), b2, voffB); PG8_STAGE(PG8_SB(0, 1), b2 + hstepB, voffB); PG8_STAGE(PG8_SA(0, 0), a2, voffA);
;             PG8_WAIT_V(8); PG8_WAIT_L(0); PG8_BAR; PG8_MMA(1, 0, At, B0); PG8_MMA(1, 1, At, B1); PG8_BAR; PG8_SCHED;
;             PG8_LDB(B0, 1, 0); PG8_LDB(B1, 1, 1); PG8_SCHED; PG8_LDA(At, 1, 0); PG8_STAGE(PG8_SA(0, 1), a2 + hstepA, voffA);
;             PG8_WAIT_V(8); PG8_WAIT_L(0); PG8_BAR; PG8_MMA(0, 0, At, B0); PG8_MMA(0, 1, At, B1); PG8_BAR; PG8_SCHED;
;             PG8_LDA(At, 1, 1); PG8_STAGE(PG8_SB(1, 0), b3, voffB); PG8_STAGE(PG8_SB(1, 1), b3 + hstepB, voffB); PG8_STAGE(PG8_SA(1, 0), a3, voffA);
;             PG8_WAIT_V(8); PG8_WAIT_L(0); PG8_BAR; PG8_MMA(1, 0, At, B0); PG8_MMA(1, 1, At, B1); PG8_BAR; PG8_SCHED;
;         }
;         if (wr == 0) PG8_BAR;
	s_add_i32 s34, s34, s13
	v_lshl_add_u64 v[200:201], v[200:201], 0, s[74:75]
	s_mov_b32 m0, s34
	ds_read_b128 v[162:165], v207 offset:49152
	ds_read_b128 v[166:169], v207 offset:50176
	ds_read_b128 v[170:173], v207 offset:51200
	ds_read_b128 v[180:183], v207 offset:52224
	ds_read_b128 v[184:187], v207 offset:53248
	ds_read_b128 v[188:191], v207 offset:54272
	ds_read_b128 v[192:195], v207 offset:55296
	ds_read_b128 v[196:199], v207 offset:56320
	global_load_lds_dwordx4 v[200:201], off
	s_add_i32 m0, s34, 0x2000
	s_add_u32 s6, s6, 0x80080
	v_lshl_add_u64 v[200:201], v[202:203], 0, s[74:75]
	s_addc_u32 s7, s7, 0
	s_add_i32 s34, s35, s13
	global_load_lds_dwordx4 v[200:201], off
	s_mov_b32 m0, s34
	v_lshl_add_u64 v[200:201], s[6:7], 0, v[0:1]
	global_load_lds_dwordx4 v[200:201], off
	s_add_i32 m0, s34, 0x2000
	v_lshl_add_u64 v[200:201], s[6:7], 0, v[174:175]
	global_load_lds_dwordx4 v[200:201], off
	s_mov_b32 m0, s91
	v_lshl_add_u64 v[200:201], v[208:209], 0, s[74:75]
	global_load_lds_dwordx4 v[200:201], off
	s_mov_b32 m0, s96
	v_lshl_add_u64 v[200:201], v[210:211], 0, s[74:75]
	global_load_lds_dwordx4 v[200:201], off
	s_waitcnt vmcnt(8) lgkmcnt(0)
	s_barrier
	v_mfma_f32_16x16x32_bf16 v[78:81], v[58:61], v[162:165], v[78:81]
	v_mfma_f32_16x16x32_bf16 v[74:77], v[66:69], v[162:165], v[74:77]
	v_mfma_f32_16x16x32_bf16 v[46:49], v[58:61], v[170:173], v[46:49]
	v_mfma_f32_16x16x32_bf16 v[42:45], v[66:69], v[170:173], v[42:45]
	v_mfma_f32_16x16x32_bf16 v[30:33], v[58:61], v[184:187], v[30:33]
	v_mfma_f32_16x16x32_bf16 v[26:29], v[66:69], v[184:187], v[26:29]
	v_mfma_f32_16x16x32_bf16 v[14:17], v[58:61], v[192:195], v[14:17]
	v_mfma_f32_16x16x32_bf16 v[10:13], v[66:69], v[192:195], v[10:13]
	v_mfma_f32_16x16x32_bf16 v[78:81], v[62:65], v[166:169], v[78:81]
	v_mfma_f32_16x16x32_bf16 v[74:77], v[70:73], v[166:169], v[74:77]
	v_mfma_f32_16x16x32_bf16 v[46:49], v[62:65], v[180:183], v[46:49]
	v_mfma_f32_16x16x32_bf16 v[42:45], v[70:73], v[180:183], v[42:45]
	v_mfma_f32_16x16x32_bf16 v[30:33], v[62:65], v[188:191], v[30:33]
	v_mfma_f32_16x16x32_bf16 v[26:29], v[70:73], v[188:191], v[26:29]
	v_mfma_f32_16x16x32_bf16 v[14:17], v[62:65], v[196:199], v[14:17]
	v_mfma_f32_16x16x32_bf16 v[10:13], v[70:73], v[196:199], v[10:13]
	v_mfma_f32_16x16x32_bf16 v[50:53], v[146:149], v[162:165], v[50:53]
	v_mfma_f32_16x16x32_bf16 v[70:73], v[150:153], v[166:169], v[50:53]
	v_mfma_f32_16x16x32_bf16 v[50:53], v[154:157], v[162:165], v[54:57]
	v_mfma_f32_16x16x32_bf16 v[38:41], v[146:149], v[170:173], v[38:41]
	v_mfma_f32_16x16x32_bf16 v[34:37], v[154:157], v[170:173], v[34:37]
	v_mfma_f32_16x16x32_bf16 v[22:25], v[146:149], v[184:187], v[22:25]
	v_mfma_f32_16x16x32_bf16 v[18:21], v[154:157], v[184:187], v[18:21]
	v_mfma_f32_16x16x32_bf16 v[6:9], v[146:149], v[192:195], v[6:9]
	v_mfma_f32_16x16x32_bf16 v[2:5], v[154:157], v[192:195], v[2:5]
	v_mfma_f32_16x16x32_bf16 v[66:69], v[158:161], v[166:169], v[50:53]
	v_mfma_f32_16x16x32_bf16 v[38:41], v[150:153], v[180:183], v[38:41]
	v_mfma_f32_16x16x32_bf16 v[34:37], v[158:161], v[180:183], v[34:37]
	v_mfma_f32_16x16x32_bf16 v[22:25], v[150:153], v[188:191], v[22:25]
	v_mfma_f32_16x16x32_bf16 v[18:21], v[158:161], v[188:191], v[18:21]
	v_mfma_f32_16x16x32_bf16 v[6:9], v[150:153], v[196:199], v[6:9]
	v_mfma_f32_16x16x32_bf16 v[2:5], v[158:161], v[196:199], v[2:5]
	s_barrier
	s_add_i32 s31, s31, 2
	s_add_u32 s29, s29, 0x100
	s_addc_u32 s30, s30, 0
	s_cmp_gt_u32 s31, 29
	s_mov_b64 s[46:47], s[4:5]
	s_cbranch_scc0 .LBB0_1199
	s_and_b64 vcc, exec, s[56:57]
	s_cbranch_vccz .LBB0_1202
	s_barrier

; template <class Epi, int AMODE>
; __device__ __forceinline__ void gemm_phase(LAS unsigned char* lds, const Gemm g, const StaticOrder& S, const Epi& E, int stagger_us, int tid_in) {
;     ...
;         for (int a = 0; a < 2; ++a)
; #pragma unroll
;             for (int b = 0; b < 2; ++b)
; #pragma unroll
;                 for (int m = 0; m < 4; ++m)
; #pragma unroll
;                     for (int n = 0; n < 2; ++n) acc[a][b][m][n] = (f32x4){0.f, 0.f, 0.f, 0.f};
;     __device__ __forceinline__ void operator()(f32x4 (&acc)[2][2][4][2], const Unit& u, int wr, int wc, int fr, int fq) const {
;     ...
;             const int tq = tok0 + 8 * fr; const int tA = tq < 0 ? 0 : (tq > TOK - 1 ? TOK - 1 : tq), tB = (tq + 7) > TOK - 1 ? TOK - 1 : (tq + 7);
;             const int bA = batch_of(tA), bB = batch_of(tB); const bool same = __all(bA == bB);
;             const float* bp0 = bias + 256 * u.pn + 32 * wc + 8 * fq;
;             f32x4 bvA[2][2]; float sq[8];
; #pragma unroll
;             for (int am = 0; am < 8; ++am) { int tok = tq + am; tok = tok < 0 ? 0 : (tok > TOK - 1 ? TOK - 1 : tok); sq[am] = LDG(float, ssq + tok); }
; #pragma unroll
;             for (int bj = 0; bj < 2; ++bj)
; #pragma unroll
;                 for (int n = 0; n < 2; ++n) bvA[bj][n] = LDG(f32x4, bp0 + (size_t)bA * (2 * DFF) + bj * HALF + 4 * n);
.LBB0_1298:
	s_ashr_i32 s47, s46, 31
	s_lshl_b64 s[6:7], s[46:47], 20
	s_add_u32 s96, s9, s6
	s_addc_u32 s97, s72, s7
	s_and_b64 s[6:7], s[42:43], exec
	s_cselect_b32 s27, s97, s5
	s_cselect_b32 s28, s96, s4
	s_add_u32 s29, s4, 0x100
	v_mov_b32_e32 v2, 0
	s_addc_u32 s30, s5, 0
	s_mov_b32 s31, -2
	s_mul_i32 s6, s26, 0xfc
	v_add_u32_e32 v222, s6, v197
	v_med3_i32 v240, v222, 0, v238
	v_add_u32_e32 v241, 0xffffe000, v240
	v_lshrrev_b32_e32 v241, 12, v241
	v_add_u32_e32 v241, 4, v241
	v_lshrrev_b32_e32 v242, 11, v240
	v_mov_b32_e32 v243, 0x2000
	v_cmp_gt_i32_e64 s[6:7], v243, v222
	s_nop 1
	v_cndmask_b32_e64 v241, v241, v242, s[6:7]
	s_lshl_b32 s6, s92, 8
	s_ashr_i32 s7, s6, 31
	v_lshl_add_u64 v[236:237], s[6:7], 2, v[184:185]
	v_mad_u64_u32 v[236:237], s[6:7], v241, s15, v[236:237]
	v_med3_i32 v224, v222, 0, v238
	v_lshlrev_b32_e32 v224, 2, v224
	global_load_dword v224, v224, s[56:57]
	v_add_u32_e32 v228, 1, v222
	v_med3_i32 v228, v228, 0, v238
	v_lshlrev_b32_e32 v228, 2, v228
	global_load_dword v228, v228, s[56:57]
	v_add_u32_e32 v231, 2, v222
	v_med3_i32 v231, v231, 0, v238
	v_lshlrev_b32_e32 v231, 2, v231
	global_load_dword v231, v231, s[56:57]
	v_add_u32_e32 v233, 3, v222
	v_med3_i32 v233, v233, 0, v238
	v_lshlrev_b32_e32 v233, 2, v233
	global_load_dword v233, v233, s[56:57]
	v_add_u32_e32 v234, 4, v222
	v_med3_i32 v234, v234, 0, v238
	v_lshlrev_b32_e32 v234, 2, v234
	global_load_dword v234, v234, s[56:57]
	v_add_u32_e32 v239, 5, v222
	v_med3_i32 v239, v239, 0, v238
	v_lshlrev_b32_e32 v239, 2, v239
	global_load_dword v239, v239, s[56:57]
	v_add_u32_e32 v252, 6, v222
	v_med3_i32 v252, v252, 0, v238
	v_lshlrev_b32_e32 v252, 2, v252
	global_load_dword v252, v252, s[56:57]
	v_add_u32_e32 v253, 7, v222
	v_med3_i32 v253, v253, 0, v238
	v_lshlrev_b32_e32 v253, 2, v253
	global_load_dword v253, v253, s[56:57]
	global_load_dwordx4 v[240:243], v[236:237], off
	global_load_dwordx4 v[244:247], v[236:237], off offset:16
	global_load_dwordx4 v[248:251], v[236:237], off offset:512
	global_load_dwordx2 v[222:223], v[236:237], off offset:528
	s_nop 0
	global_load_dwordx2 v[236:237], v[236:237], off offset:536
	v_mov_b32_e32 v3, v2
	v_mov_b32_e32 v4, v2
	v_mov_b32_e32 v5, v2
	v_mov_b32_e32 v14, v2
	v_mov_b32_e32 v15, v2
	v_mov_b32_e32 v16, v2
	v_mov_b32_e32 v17, v2
	v_mov_b32_e32 v10, v2
	v_mov_b32_e32 v11, v2
	v_mov_b32_e32 v12, v2
	v_mov_b32_e32 v13, v2
	v_mov_b32_e32 v26, v2
	v_mov_b32_e32 v27, v2
	v_mov_b32_e32 v28, v2
	v_mov_b32_e32 v29, v2
	v_mov_b32_e32 v6, v2
	v_mov_b32_e32 v7, v2
	v_mov_b32_e32 v8, v2
	v_mov_b32_e32 v9, v2
	v_mov_b32_e32 v42, v2
	v_mov_b32_e32 v43, v2
	v_mov_b32_e32 v44, v2
	v_mov_b32_e32 v45, v2
	v_mov_b32_e32 v30, v2
	v_mov_b32_e32 v31, v2
	v_mov_b32_e32 v32, v2
	v_mov_b32_e32 v33, v2
	v_mov_b32_e32 v58, v2
	v_mov_b32_e32 v59, v2
	v_mov_b32_e32 v60, v2
	v_mov_b32_e32 v61, v2
	v_mov_b32_e32 v74, v2
	v_mov_b32_e32 v75, v2
	v_mov_b32_e32 v76, v2
	v_mov_b32_e32 v77, v2
	v_mov_b32_e32 v22, v2
	v_mov_b32_e32 v23, v2
	v_mov_b32_e32 v24, v2
	v_mov_b32_e32 v25, v2
	v_mov_b32_e32 v34, v2
	v_mov_b32_e32 v35, v2
	v_mov_b32_e32 v36, v2
	v_mov_b32_e32 v37, v2
	v_mov_b32_e32 v18, v2
	v_mov_b32_e32 v19, v2
	v_mov_b32_e32 v20, v2
	v_mov_b32_e32 v21, v2
	v_mov_b32_e32 v50, v2
	v_mov_b32_e32 v51, v2
	v_mov_b32_e32 v52, v2
	v_mov_b32_e32 v53, v2
	v_mov_b32_e32 v38, v2
	v_mov_b32_e32 v39, v2
	v_mov_b32_e32 v40, v2
	v_mov_b32_e32 v41, v2
	v_mov_b32_e32 v46, v2
	v_mov_b32_e32 v47, v2
	v_mov_b32_e32 v48, v2
	v_mov_b32_e32 v49, v2
	v_mov_b32_e32 v54, v2
	v_mov_b32_e32 v55, v2
	v_mov_b32_e32 v56, v2
	v_mov_b32_e32 v57, v2
	v_mov_b32_e32 v66, v2
	v_mov_b32_e32 v67, v2
	v_mov_b32_e32 v68, v2
	v_mov_b32_e32 v69, v2
	v_mov_b32_e32 v78, v2
	v_mov_b32_e32 v79, v2
	v_mov_b32_e32 v80, v2
	v_mov_b32_e32 v81, v2
	v_mov_b32_e32 v62, v2
	v_mov_b32_e32 v63, v2
	v_mov_b32_e32 v64, v2
	v_mov_b32_e32 v65, v2
	v_mov_b32_e32 v70, v2
	v_mov_b32_e32 v71, v2
	v_mov_b32_e32 v72, v2
	v_mov_b32_e32 v73, v2
	v_mov_b32_e32 v86, v2
	v_mov_b32_e32 v87, v2
	v_mov_b32_e32 v88, v2
	v_mov_b32_e32 v89, v2
	v_mov_b32_e32 v94, v2
	v_mov_b32_e32 v95, v2
	v_mov_b32_e32 v96, v2
	v_mov_b32_e32 v97, v2
	v_mov_b32_e32 v98, v2
	v_mov_b32_e32 v99, v2
	v_mov_b32_e32 v100, v2
	v_mov_b32_e32 v101, v2
	v_mov_b32_e32 v106, v2
	v_mov_b32_e32 v107, v2
	v_mov_b32_e32 v108, v2
	v_mov_b32_e32 v109, v2
	v_mov_b32_e32 v82, v2
	v_mov_b32_e32 v83, v2
	v_mov_b32_e32 v84, v2
	v_mov_b32_e32 v85, v2
	v_mov_b32_e32 v90, v2
	v_mov_b32_e32 v91, v2
	v_mov_b32_e32 v92, v2
	v_mov_b32_e32 v93, v2
	v_mov_b32_e32 v102, v2
	v_mov_b32_e32 v103, v2
	v_mov_b32_e32 v104, v2
	v_mov_b32_e32 v105, v2
	v_mov_b32_e32 v110, v2
	v_mov_b32_e32 v111, v2
	v_mov_b32_e32 v112, v2
	v_mov_b32_e32 v113, v2
	v_mov_b32_e32 v114, v2
	v_mov_b32_e32 v115, v2
	v_mov_b32_e32 v116, v2
	v_mov_b32_e32 v117, v2
	v_mov_b32_e32 v118, v2
	v_mov_b32_e32 v119, v2
	v_mov_b32_e32 v120, v2
	v_mov_b32_e32 v121, v2
	v_mov_b32_e32 v122, v2
	v_mov_b32_e32 v123, v2
	v_mov_b32_e32 v124, v2
	v_mov_b32_e32 v125, v2
	v_mov_b32_e32 v126, v2
	v_mov_b32_e32 v127, v2
	v_mov_b32_e32 v128, v2
	v_mov_b32_e32 v129, v2
	s_add_u32 s4, s44, 0x100
	s_addc_u32 s5, s45, 0
	s_add_i32 s34, 0, 0x10000
	s_cmp_eq_u32 s31, 28
	s_cselect_b32 s43, s95, s5
	s_cselect_b32 s42, s94, s4
	s_cselect_b32 s7, s27, s30
	s_cselect_b32 s6, s28, s29
	s_add_i32 s35, 0, 0x14000
	v_add_u32_e32 v142, s34, v196
	v_add_u32_e32 v158, s35, v196
	ds_read_b128 v[130:133], v142
	ds_read_b128 v[134:137], v142 offset:1024
	ds_read_b128 v[138:141], v142 offset:2048
	ds_read_b128 v[142:145], v142 offset:3072
	ds_read_b128 v[146:149], v158
	ds_read_b128 v[150:153], v158 offset:1024
	ds_read_b128 v[154:157], v158 offset:2048
	ds_read_b128 v[158:161], v158 offset:3072
	v_lshl_add_u64 v[194:195], s[44:45], 0, v[186:187]
	s_add_i32 m0, s93, 0xc000
	ds_read_b128 v[162:165], v201
	ds_read_b128 v[166:169], v201 offset:1024
	ds_read_b128 v[170:173], v201 offset:2048
	ds_read_b128 v[174:177], v201 offset:3072
	ds_read_b128 v[190:193], v201 offset:4096
	ds_read_b128 v[202:205], v201 offset:5120
	ds_read_b128 v[206:209], v201 offset:6144
	ds_read_b128 v[210:213], v201 offset:7168
	global_load_lds_dwordx4 v[194:195], off
	s_add_i32 m0, s93, 0xe000
	v_lshl_add_u64 v[194:195], s[44:45], 0, v[188:189]
	global_load_lds_dwordx4 v[194:195], off
	s_waitcnt lgkmcnt(0)
	s_barrier
; #define PG8_STAGE(bufoff, gbase, voff) do { _Pragma("unroll") for (int _i = 0; _i < 2; ++_i) \
;         __builtin_amdgcn_global_load_lds((const unsigned*)((const char*)(gbase) + (voff)[_i]), (LAS unsigned*)(lds + (bufoff) + ldsw + _i * 8192), 16, 0, 0); } while (0)
; #define PG8_LDA(dst, b, h) do { _Pragma("unroll") for (int m = 0; m < 4; ++m) _Pragma("unroll") for (int k = 0; k < 2; ++k) dst[m][k] = *(const LAS bf16x8*)(lds + PG8_SA(b, h) + aoff + m * 2048 + k * 1024); } while (0)
; #define PG8_LDB(dst, b, h) do { _Pragma("unroll") for (int n = 0; n < 2; ++n) _Pragma("unroll") for (int k = 0; k < 2; ++k) dst[n][k] = *(const LAS bf16x8*)(lds + PG8_SB(b, h) + boff + n * 2048 + k * 1024); } while (0)
; #define PG8_WAIT_V(n) asm volatile("s_waitcnt vmcnt(" #n ")" ::: "memory")
; template <class Epi, int AMODE>
; __device__ __forceinline__ void gemm_phase(LAS unsigned char* lds, const Gemm g, const StaticOrder& S, const Epi& E, int stagger_us, int tid_in) {
;     ...
;         for (int t = 0; t < nt; t += 2) {
;             const bool last = (t == nt - 2);
;             const char* a1 = cA + (size_t)(t + 1) * kstep;
;             const char* a2 = last ? nA : cA + (size_t)(t + 2) * kstep; const char* b2 = last ? nB : cB + (size_t)(t + 2) * kstep;
;             const char* a3 = a2 + kstep; const char* b3 = b2 + kstep;
;             PG8_LDB(B0, 0, 0); PG8_LDB(B1, 0, 1); PG8_SCHED; PG8_LDA(At, 0, 0); PG8_STAGE(PG8_SA(1, 1), a1 + hstepA, voffA);
;             PG8_WAIT_V(8); PG8_WAIT_L(0); PG8_BAR; PG8_MMA(0, 0, At, B0); PG8_MMA(0, 1, At, B1); PG8_BAR; PG8_SCHED;
;             PG8_LDA(At, 0, 1); PG8_STAGE(PG8_SB(0, 0), b2, voffB); PG8_STAGE(PG8_SB(0, 1), b2 + hstepB, voffB); PG8_STAGE(PG8_SA(0, 0), a2, voffA);
;             PG8_WAIT_V(8); PG8_WAIT_L(0); PG8_BAR; PG8_MMA(1, 0, At, B0); PG8_MMA(1, 1, At, B1); PG8_BAR; PG8_SCHED;
;             PG8_LDB(B0, 1, 0); PG8_LDB(B1, 1, 1); PG8_SCHED; PG8_LDA(At, 1, 0); PG8_STAGE(PG8_SA(0, 1), a2 + hstepA, voffA);
;             PG8_WAIT_V(8); PG8_WAIT_L(0); PG8_BAR; PG8_MMA(0, 0, At, B0); PG8_MMA(0, 1, At, B1); PG8_BAR; PG8_SCHED;
;             PG8_LDA(At, 1, 1); PG8_STAGE(PG8_SB(1, 0), b3, voffB); PG8_STAGE(PG8_SB(1, 1), b3 + hstepB, voffB); PG8_STAGE(PG8_SA(1, 0), a3, voffA);
;             PG8_WAIT_V(8); PG8_WAIT_L(0); PG8_BAR; PG8_MMA(1, 0, At, B0); PG8_MMA(1, 1, At, B1); PG8_BAR; PG8_SCHED;
	v_mfma_f32_16x16x32_bf16 v[126:129], v[130:133], v[162:165], v[126:129]
	v_mfma_f32_16x16x32_bf16 v[122:125], v[138:141], v[162:165], v[122:125]
	v_mfma_f32_16x16x32_bf16 v[118:121], v[130:133], v[170:173], v[118:121]
	v_mfma_f32_16x16x32_bf16 v[114:117], v[138:141], v[170:173], v[114:117]
	v_mfma_f32_16x16x32_bf16 v[110:113], v[130:133], v[190:193], v[110:113]
	v_mfma_f32_16x16x32_bf16 v[102:105], v[138:141], v[190:193], v[102:105]
	v_mfma_f32_16x16x32_bf16 v[90:93], v[130:133], v[206:209], v[90:93]
	v_mfma_f32_16x16x32_bf16 v[82:85], v[138:141], v[206:209], v[82:85]
	v_mfma_f32_16x16x32_bf16 v[126:129], v[134:137], v[166:169], v[126:129]
	v_mfma_f32_16x16x32_bf16 v[122:125], v[142:145], v[166:169], v[122:125]
	v_mfma_f32_16x16x32_bf16 v[118:121], v[134:137], v[174:177], v[118:121]
	v_mfma_f32_16x16x32_bf16 v[114:117], v[142:145], v[174:177], v[114:117]
	v_mfma_f32_16x16x32_bf16 v[110:113], v[134:137], v[202:205], v[110:113]
	v_mfma_f32_16x16x32_bf16 v[102:105], v[142:145], v[202:205], v[102:105]
	v_mfma_f32_16x16x32_bf16 v[90:93], v[134:137], v[210:213], v[90:93]
	v_mfma_f32_16x16x32_bf16 v[82:85], v[142:145], v[210:213], v[82:85]
	v_mfma_f32_16x16x32_bf16 v[106:109], v[146:149], v[162:165], v[106:109]
	v_mfma_f32_16x16x32_bf16 v[98:101], v[154:157], v[162:165], v[98:101]
	v_mfma_f32_16x16x32_bf16 v[94:97], v[146:149], v[170:173], v[94:97]
	v_mfma_f32_16x16x32_bf16 v[86:89], v[154:157], v[170:173], v[86:89]
	v_mfma_f32_16x16x32_bf16 v[70:73], v[146:149], v[190:193], v[70:73]
	v_mfma_f32_16x16x32_bf16 v[62:65], v[154:157], v[190:193], v[62:65]
	v_mfma_f32_16x16x32_bf16 v[78:81], v[146:149], v[206:209], v[78:81]
	v_mfma_f32_16x16x32_bf16 v[66:69], v[154:157], v[206:209], v[66:69]
	v_mfma_f32_16x16x32_bf16 v[106:109], v[150:153], v[166:169], v[106:109]
	v_mfma_f32_16x16x32_bf16 v[98:101], v[158:161], v[166:169], v[98:101]
	v_mfma_f32_16x16x32_bf16 v[94:97], v[150:153], v[174:177], v[94:97]
	v_mfma_f32_16x16x32_bf16 v[86:89], v[158:161], v[174:177], v[86:89]
	v_mfma_f32_16x16x32_bf16 v[70:73], v[150:153], v[202:205], v[70:73]
	v_mfma_f32_16x16x32_bf16 v[62:65], v[158:161], v[202:205], v[62:65]
	v_mfma_f32_16x16x32_bf16 v[78:81], v[150:153], v[210:213], v[78:81]
	v_mfma_f32_16x16x32_bf16 v[66:69], v[158:161], v[210:213], v[66:69]
	s_barrier
	s_add_i32 s34, s34, s91
	v_lshl_add_u64 v[194:195], s[6:7], 0, v[0:1]
	s_mov_b32 m0, s34
	ds_read_b128 v[162:165], v201 offset:16384
	ds_read_b128 v[166:169], v201 offset:17408
	ds_read_b128 v[170:173], v201 offset:18432
	ds_read_b128 v[174:177], v201 offset:19456
	ds_read_b128 v[190:193], v201 offset:20480
	ds_read_b128 v[202:205], v201 offset:21504
	ds_read_b128 v[206:209], v201 offset:22528
	ds_read_b128 v[210:213], v201 offset:23552
	global_load_lds_dwordx4 v[194:195], off
	s_add_i32 m0, s34, 0x2000
	s_add_u32 s44, s6, 0x80000
	v_lshl_add_u64 v[214:215], s[6:7], 0, v[182:183]
	s_addc_u32 s45, s7, 0
	s_add_i32 s34, s35, s91
	global_load_lds_dwordx4 v[214:215], off
	v_lshl_add_u64 v[216:217], s[44:45], 0, v[0:1]
	s_mov_b32 m0, s34
	v_lshl_add_u64 v[218:219], s[42:43], 0, v[180:181]
	global_load_lds_dwordx4 v[216:217], off
	s_add_i32 m0, s34, 0x2000
	v_lshl_add_u64 v[216:217], s[44:45], 0, v[182:183]
	global_load_lds_dwordx4 v[216:217], off
	s_mov_b32 m0, s93
	v_lshl_add_u64 v[216:217], s[42:43], 0, v[178:179]
	global_load_lds_dwordx4 v[216:217], off
	s_mov_b32 m0, s83
	s_nop 0
	global_load_lds_dwordx4 v[218:219], off
	s_waitcnt lgkmcnt(0)
	s_barrier
	v_mfma_f32_16x16x32_bf16 v[54:57], v[130:133], v[162:165], v[54:57]
	v_mfma_f32_16x16x32_bf16 v[46:49], v[138:141], v[162:165], v[46:49]
	v_mfma_f32_16x16x32_bf16 v[38:41], v[130:133], v[170:173], v[38:41]
	v_mfma_f32_16x16x32_bf16 v[50:53], v[138:141], v[170:173], v[50:53]
	v_mfma_f32_16x16x32_bf16 v[18:21], v[130:133], v[190:193], v[18:21]
	v_mfma_f32_16x16x32_bf16 v[34:37], v[138:141], v[190:193], v[34:37]
	v_mfma_f32_16x16x32_bf16 v[22:25], v[130:133], v[206:209], v[22:25]
	v_mfma_f32_16x16x32_bf16 v[74:77], v[138:141], v[206:209], v[74:77]
	v_mfma_f32_16x16x32_bf16 v[54:57], v[134:137], v[166:169], v[54:57]
	v_mfma_f32_16x16x32_bf16 v[46:49], v[142:145], v[166:169], v[46:49]
	v_mfma_f32_16x16x32_bf16 v[38:41], v[134:137], v[174:177], v[38:41]
	v_mfma_f32_16x16x32_bf16 v[50:53], v[142:145], v[174:177], v[50:53]
	v_mfma_f32_16x16x32_bf16 v[18:21], v[134:137], v[202:205], v[18:21]
	v_mfma_f32_16x16x32_bf16 v[34:37], v[142:145], v[202:205], v[34:37]
	v_mfma_f32_16x16x32_bf16 v[22:25], v[134:137], v[210:213], v[22:25]
	v_mfma_f32_16x16x32_bf16 v[74:77], v[142:145], v[210:213], v[74:77]
	v_mfma_f32_16x16x32_bf16 v[58:61], v[146:149], v[162:165], v[58:61]
	v_mfma_f32_16x16x32_bf16 v[30:33], v[154:157], v[162:165], v[30:33]
	v_mfma_f32_16x16x32_bf16 v[42:45], v[146:149], v[170:173], v[42:45]
	v_mfma_f32_16x16x32_bf16 v[6:9], v[154:157], v[170:173], v[6:9]
	v_mfma_f32_16x16x32_bf16 v[26:29], v[146:149], v[190:193], v[26:29]
	v_mfma_f32_16x16x32_bf16 v[10:13], v[154:157], v[190:193], v[10:13]
	v_mfma_f32_16x16x32_bf16 v[14:17], v[146:149], v[206:209], v[14:17]
	v_mfma_f32_16x16x32_bf16 v[2:5], v[154:157], v[206:209], v[2:5]
	v_mfma_f32_16x16x32_bf16 v[58:61], v[150:153], v[166:169], v[58:61]
	v_mfma_f32_16x16x32_bf16 v[30:33], v[158:161], v[166:169], v[30:33]
	v_mfma_f32_16x16x32_bf16 v[42:45], v[150:153], v[174:177], v[42:45]
	v_mfma_f32_16x16x32_bf16 v[6:9], v[158:161], v[174:177], v[6:9]
	v_mfma_f32_16x16x32_bf16 v[26:29], v[150:153], v[202:205], v[26:29]
	v_mfma_f32_16x16x32_bf16 v[10:13], v[158:161], v[202:205], v[10:13]
	v_mfma_f32_16x16x32_bf16 v[14:17], v[150:153], v[210:213], v[14:17]
	v_mfma_f32_16x16x32_bf16 v[2:5], v[158:161], v[210:213], v[2:5]
	s_barrier
; #define PG8_STAGE(bufoff, gbase, voff) do { _Pragma("unroll") for (int _i = 0; _i < 2; ++_i) \
;         __builtin_amdgcn_global_load_lds((const unsigned*)((const char*)(gbase) + (voff)[_i]), (LAS unsigned*)(lds + (bufoff) + ldsw + _i * 8192), 16, 0, 0); } while (0)
; #define PG8_LDA(dst, b, h) do { _Pragma("unroll") for (int m = 0; m < 4; ++m) _Pragma("unroll") for (int k = 0; k < 2; ++k) dst[m][k] = *(const LAS bf16x8*)(lds + PG8_SA(b, h) + aoff + m * 2048 + k * 1024); } while (0)
; #define PG8_LDB(dst, b, h) do { _Pragma("unroll") for (int n = 0; n < 2; ++n) _Pragma("unroll") for (int k = 0; k < 2; ++k) dst[n][k] = *(const LAS bf16x8*)(lds + PG8_SB(b, h) + boff + n * 2048 + k * 1024); } while (0)
; #define PG8_WAIT_V(n) asm volatile("s_waitcnt vmcnt(" #n ")" ::: "memory")
; template <class Epi, int AMODE>
; __device__ __forceinline__ void gemm_phase(LAS unsigned char* lds, const Gemm g, const StaticOrder& S, const Epi& E, int stagger_us, int tid_in) {
;     ...
;         for (int t = 0; t < nt; t += 2) {
;             const bool last = (t == nt - 2);
;             const char* a1 = cA + (size_t)(t + 1) * kstep;
;             const char* a2 = last ? nA : cA + (size_t)(t + 2) * kstep; const char* b2 = last ? nB : cB + (size_t)(t + 2) * kstep;
;             const char* a3 = a2 + kstep; const char* b3 = b2 + kstep;
;             PG8_LDB(B0, 0, 0); PG8_LDB(B1, 0, 1); PG8_SCHED; PG8_LDA(At, 0, 0); PG8_STAGE(PG8_SA(1, 1), a1 + hstepA, voffA);
;             PG8_WAIT_V(8); PG8_WAIT_L(0); PG8_BAR; PG8_MMA(0, 0, At, B0); PG8_MMA(0, 1, At, B1); PG8_BAR; PG8_SCHED;
;             PG8_LDA(At, 0, 1); PG8_STAGE(PG8_SB(0, 0), b2, voffB); PG8_STAGE(PG8_SB(0, 1), b2 + hstepB, voffB); PG8_STAGE(PG8_SA(0, 0), a2, voffA);
;             PG8_WAIT_V(8); PG8_WAIT_L(0); PG8_BAR; PG8_MMA(1, 0, At, B0); PG8_MMA(1, 1, At, B1); PG8_BAR; PG8_SCHED;
;             PG8_LDB(B0, 1, 0); PG8_LDB(B1, 1, 1); PG8_SCHED; PG8_LDA(At, 1, 0); PG8_STAGE(PG8_SA(0, 1), a2 + hstepA, voffA);
;             PG8_WAIT_V(8); PG8_WAIT_L(0); PG8_BAR; PG8_MMA(0, 0, At, B0); PG8_MMA(0, 1, At, B1); PG8_BAR; PG8_SCHED;
;             PG8_LDA(At, 1, 1); PG8_STAGE(PG8_SB(1, 0), b3, voffB); PG8_STAGE(PG8_SB(1, 1), b3 + hstepB, voffB); PG8_STAGE(PG8_SA(1, 0), a3, voffA);
;             PG8_WAIT_V(8); PG8_WAIT_L(0); PG8_BAR; PG8_MMA(1, 0, At, B0); PG8_MMA(1, 1, At, B1); PG8_BAR; PG8_SCHED;
	s_add_i32 s34, 0, 0x18000
	s_add_i32 s35, 0, 0x1c000
	v_add_u32_e32 v142, s34, v196
	v_add_u32_e32 v158, s35, v196
	ds_read_b128 v[130:133], v142
	ds_read_b128 v[134:137], v142 offset:1024
	ds_read_b128 v[138:141], v142 offset:2048
	ds_read_b128 v[142:145], v142 offset:3072
	ds_read_b128 v[146:149], v158
	ds_read_b128 v[150:153], v158 offset:1024
	ds_read_b128 v[154:157], v158 offset:2048
	ds_read_b128 v[158:161], v158 offset:3072
	s_add_u32 s42, s42, 0x4000
	s_addc_u32 s43, s43, 0
	s_mov_b32 m0, s79
	v_lshl_add_u64 v[220:221], s[42:43], 0, v[178:179]
	ds_read_b128 v[162:165], v201 offset:32768
	ds_read_b128 v[166:169], v201 offset:33792
	ds_read_b128 v[170:173], v201 offset:34816
	ds_read_b128 v[174:177], v201 offset:35840
	ds_read_b128 v[190:193], v201 offset:36864
	ds_read_b128 v[202:205], v201 offset:37888
	ds_read_b128 v[206:209], v201 offset:38912
	ds_read_b128 v[210:213], v201 offset:39936
	global_load_lds_dwordx4 v[220:221], off
	s_mov_b32 m0, s87
	v_lshl_add_u64 v[220:221], s[42:43], 0, v[180:181]
	global_load_lds_dwordx4 v[220:221], off
	s_waitcnt vmcnt(8) lgkmcnt(0)
	s_barrier
	v_mfma_f32_16x16x32_bf16 v[126:129], v[130:133], v[162:165], v[126:129]
	v_mfma_f32_16x16x32_bf16 v[122:125], v[138:141], v[162:165], v[122:125]
	v_mfma_f32_16x16x32_bf16 v[118:121], v[130:133], v[170:173], v[118:121]
	v_mfma_f32_16x16x32_bf16 v[114:117], v[138:141], v[170:173], v[114:117]
	v_mfma_f32_16x16x32_bf16 v[110:113], v[130:133], v[190:193], v[110:113]
	v_mfma_f32_16x16x32_bf16 v[102:105], v[138:141], v[190:193], v[102:105]
	v_mfma_f32_16x16x32_bf16 v[90:93], v[130:133], v[206:209], v[90:93]
	v_mfma_f32_16x16x32_bf16 v[82:85], v[138:141], v[206:209], v[82:85]
	v_mfma_f32_16x16x32_bf16 v[126:129], v[134:137], v[166:169], v[126:129]
	v_mfma_f32_16x16x32_bf16 v[122:125], v[142:145], v[166:169], v[122:125]
	v_mfma_f32_16x16x32_bf16 v[118:121], v[134:137], v[174:177], v[118:121]
	v_mfma_f32_16x16x32_bf16 v[114:117], v[142:145], v[174:177], v[114:117]
	v_mfma_f32_16x16x32_bf16 v[110:113], v[134:137], v[202:205], v[110:113]
	v_mfma_f32_16x16x32_bf16 v[102:105], v[142:145], v[202:205], v[102:105]
	v_mfma_f32_16x16x32_bf16 v[90:93], v[134:137], v[210:213], v[90:93]
	v_mfma_f32_16x16x32_bf16 v[82:85], v[142:145], v[210:213], v[82:85]
	v_mfma_f32_16x16x32_bf16 v[106:109], v[146:149], v[162:165], v[106:109]
	v_mfma_f32_16x16x32_bf16 v[98:101], v[154:157], v[162:165], v[98:101]
	v_mfma_f32_16x16x32_bf16 v[94:97], v[146:149], v[170:173], v[94:97]
	v_mfma_f32_16x16x32_bf16 v[86:89], v[154:157], v[170:173], v[86:89]
	v_mfma_f32_16x16x32_bf16 v[70:73], v[146:149], v[190:193], v[70:73]
	v_mfma_f32_16x16x32_bf16 v[62:65], v[154:157], v[190:193], v[62:65]
	v_mfma_f32_16x16x32_bf16 v[78:81], v[146:149], v[206:209], v[78:81]
	v_mfma_f32_16x16x32_bf16 v[66:69], v[154:157], v[206:209], v[66:69]
	v_mfma_f32_16x16x32_bf16 v[106:109], v[150:153], v[166:169], v[106:109]
	v_mfma_f32_16x16x32_bf16 v[98:101], v[158:161], v[166:169], v[98:101]
	v_mfma_f32_16x16x32_bf16 v[94:97], v[150:153], v[174:177], v[94:97]
	v_mfma_f32_16x16x32_bf16 v[86:89], v[158:161], v[174:177], v[86:89]
	v_mfma_f32_16x16x32_bf16 v[70:73], v[150:153], v[202:205], v[70:73]
	v_mfma_f32_16x16x32_bf16 v[62:65], v[158:161], v[202:205], v[62:65]
	v_mfma_f32_16x16x32_bf16 v[78:81], v[150:153], v[210:213], v[78:81]
	v_mfma_f32_16x16x32_bf16 v[66:69], v[158:161], v[210:213], v[66:69]
	s_barrier
	s_add_i32 s34, s34, s91
	v_lshl_add_u64 v[194:195], v[194:195], 0, s[74:75]
	s_mov_b32 m0, s34
	ds_read_b128 v[162:165], v201 offset:49152
	ds_read_b128 v[166:169], v201 offset:50176
	ds_read_b128 v[170:173], v201 offset:51200
	ds_read_b128 v[174:177], v201 offset:52224
	ds_read_b128 v[190:193], v201 offset:53248
	ds_read_b128 v[202:205], v201 offset:54272
	ds_read_b128 v[206:209], v201 offset:55296
	ds_read_b128 v[210:213], v201 offset:56320
	global_load_lds_dwordx4 v[194:195], off
	s_add_i32 m0, s34, 0x2000
	s_add_u32 s6, s6, 0x80080
	v_lshl_add_u64 v[194:195], v[214:215], 0, s[74:75]
	s_addc_u32 s7, s7, 0
	s_add_i32 s34, s35, s91
	global_load_lds_dwordx4 v[194:195], off
	s_mov_b32 m0, s34
	v_lshl_add_u64 v[194:195], s[6:7], 0, v[0:1]
	global_load_lds_dwordx4 v[194:195], off
	s_add_i32 m0, s34, 0x2000
	v_lshl_add_u64 v[194:195], s[6:7], 0, v[182:183]
	global_load_lds_dwordx4 v[194:195], off
	s_mov_b32 m0, s67
	v_lshl_add_u64 v[194:195], v[216:217], 0, s[74:75]
	global_load_lds_dwordx4 v[194:195], off
	s_mov_b32 m0, s85
	v_lshl_add_u64 v[194:195], v[218:219], 0, s[74:75]
	global_load_lds_dwordx4 v[194:195], off
	s_waitcnt vmcnt(8) lgkmcnt(0)
	s_barrier
	v_mfma_f32_16x16x32_bf16 v[54:57], v[130:133], v[162:165], v[54:57]
	v_mfma_f32_16x16x32_bf16 v[46:49], v[138:141], v[162:165], v[46:49]
	v_mfma_f32_16x16x32_bf16 v[38:41], v[130:133], v[170:173], v[38:41]
	v_mfma_f32_16x16x32_bf16 v[50:53], v[138:141], v[170:173], v[50:53]
	v_mfma_f32_16x16x32_bf16 v[18:21], v[130:133], v[190:193], v[18:21]
	v_mfma_f32_16x16x32_bf16 v[34:37], v[138:141], v[190:193], v[34:37]
	v_mfma_f32_16x16x32_bf16 v[22:25], v[130:133], v[206:209], v[22:25]
	v_mfma_f32_16x16x32_bf16 v[74:77], v[138:141], v[206:209], v[74:77]
	v_mfma_f32_16x16x32_bf16 v[54:57], v[134:137], v[166:169], v[54:57]
	v_mfma_f32_16x16x32_bf16 v[46:49], v[142:145], v[166:169], v[46:49]
	v_mfma_f32_16x16x32_bf16 v[38:41], v[134:137], v[174:177], v[38:41]
	v_mfma_f32_16x16x32_bf16 v[50:53], v[142:145], v[174:177], v[50:53]
	v_mfma_f32_16x16x32_bf16 v[18:21], v[134:137], v[202:205], v[18:21]
	v_mfma_f32_16x16x32_bf16 v[34:37], v[142:145], v[202:205], v[34:37]
	v_mfma_f32_16x16x32_bf16 v[22:25], v[134:137], v[210:213], v[22:25]
	v_mfma_f32_16x16x32_bf16 v[74:77], v[142:145], v[210:213], v[74:77]
	v_mfma_f32_16x16x32_bf16 v[58:61], v[146:149], v[162:165], v[58:61]
	v_mfma_f32_16x16x32_bf16 v[30:33], v[154:157], v[162:165], v[30:33]
	v_mfma_f32_16x16x32_bf16 v[42:45], v[146:149], v[170:173], v[42:45]
	v_mfma_f32_16x16x32_bf16 v[6:9], v[154:157], v[170:173], v[6:9]
	v_mfma_f32_16x16x32_bf16 v[26:29], v[146:149], v[190:193], v[26:29]
	v_mfma_f32_16x16x32_bf16 v[10:13], v[154:157], v[190:193], v[10:13]
	v_mfma_f32_16x16x32_bf16 v[14:17], v[146:149], v[206:209], v[14:17]
	v_mfma_f32_16x16x32_bf16 v[2:5], v[154:157], v[206:209], v[2:5]
	v_mfma_f32_16x16x32_bf16 v[58:61], v[150:153], v[166:169], v[58:61]
	v_mfma_f32_16x16x32_bf16 v[30:33], v[158:161], v[166:169], v[30:33]
	v_mfma_f32_16x16x32_bf16 v[42:45], v[150:153], v[174:177], v[42:45]
	v_mfma_f32_16x16x32_bf16 v[6:9], v[158:161], v[174:177], v[6:9]
	v_mfma_f32_16x16x32_bf16 v[26:29], v[150:153], v[202:205], v[26:29]
	v_mfma_f32_16x16x32_bf16 v[10:13], v[158:161], v[202:205], v[10:13]
	v_mfma_f32_16x16x32_bf16 v[14:17], v[150:153], v[210:213], v[14:17]
	v_mfma_f32_16x16x32_bf16 v[2:5], v[158:161], v[210:213], v[2:5]
	s_barrier
	s_add_i32 s31, s31, 2
	s_add_u32 s29, s29, 0x100
	s_addc_u32 s30, s30, 0
	s_cmp_gt_u32 s31, 29
	s_mov_b64 s[44:45], s[4:5]
; #define PG8_STAGE(bufoff, gbase, voff) do { _Pragma("unroll") for (int _i = 0; _i < 2; ++_i) \
;         __builtin_amdgcn_global_load_lds((const unsigned*)((const char*)(gbase) + (voff)[_i]), (LAS unsigned*)(lds + (bufoff) + ldsw + _i * 8192), 16, 0, 0); } while (0)
; #define PG8_LDA(dst, b, h) do { _Pragma("unroll") for (int m = 0; m < 4; ++m) _Pragma("unroll") for (int k = 0; k < 2; ++k) dst[m][k] = *(const LAS bf16x8*)(lds + PG8_SA(b, h) + aoff + m * 2048 + k * 1024); } while (0)
; #define PG8_LDB(dst, b, h) do { _Pragma("unroll") for (int n = 0; n < 2; ++n) _Pragma("unroll") for (int k = 0; k < 2; ++k) dst[n][k] = *(const LAS bf16x8*)(lds + PG8_SB(b, h) + boff + n * 2048 + k * 1024); } while (0)
; #define PG8_WAIT_V(n) asm volatile("s_waitcnt vmcnt(" #n ")" ::: "memory")
; template <class Epi, int AMODE>
; __device__ __forceinline__ void gemm_phase(LAS unsigned char* lds, const Gemm g, const StaticOrder& S, const Epi& E, int stagger_us, int tid_in) {
;     ...
;         for (int t = 0; t < nt; t += 2) {
;             const bool last = (t == nt - 2);
;             const char* a1 = cA + (size_t)(t + 1) * kstep;
;             const char* a2 = last ? nA : cA + (size_t)(t + 2) * kstep; const char* b2 = last ? nB : cB + (size_t)(t + 2) * kstep;
;             const char* a3 = a2 + kstep; const char* b3 = b2 + kstep;
;             PG8_LDB(B0, 0, 0); PG8_LDB(B1, 0, 1); PG8_SCHED; PG8_LDA(At, 0, 0); PG8_STAGE(PG8_SA(1, 1), a1 + hstepA, voffA);
;             PG8_WAIT_V(8); PG8_WAIT_L(0); PG8_BAR; PG8_MMA(0, 0, At, B0); PG8_MMA(0, 1, At, B1); PG8_BAR; PG8_SCHED;
;             PG8_LDA(At, 0, 1); PG8_STAGE(PG8_SB(0, 0), b2, voffB); PG8_STAGE(PG8_SB(0, 1), b2 + hstepB, voffB); PG8_STAGE(PG8_SA(0, 0), a2, voffA);
;             PG8_WAIT_V(8); PG8_WAIT_L(0); PG8_BAR; PG8_MMA(1, 0, At, B0); PG8_MMA(1, 1, At, B1); PG8_BAR; PG8_SCHED;
;             PG8_LDB(B0, 1, 0); PG8_LDB(B1, 1, 1); PG8_SCHED; PG8_LDA(At, 1, 0); PG8_STAGE(PG8_SA(0, 1), a2 + hstepA, voffA);
;             PG8_WAIT_V(8); PG8_WAIT_L(0); PG8_BAR; PG8_MMA(0, 0, At, B0); PG8_MMA(0, 1, At, B1); PG8_BAR; PG8_SCHED;
;             PG8_LDA(At, 1, 1); PG8_STAGE(PG8_SB(1, 0), b3, voffB); PG8_STAGE(PG8_SB(1, 1), b3 + hstepB, voffB); PG8_STAGE(PG8_SA(1, 0), a3, voffA);
;             PG8_WAIT_V(8); PG8_WAIT_L(0); PG8_BAR; PG8_MMA(1, 0, At, B0); PG8_MMA(1, 1, At, B1); PG8_BAR; PG8_SCHED;
.LBB0_1299:
	s_add_u32 s4, s44, 0x100
	s_addc_u32 s5, s45, 0
	s_add_i32 s34, 0, 0x10000
	s_cmp_eq_u32 s31, 28
	s_cselect_b32 s43, s95, s5
	s_cselect_b32 s42, s94, s4
	s_cselect_b32 s7, s27, s30
	s_cselect_b32 s6, s28, s29
	s_add_i32 s35, 0, 0x14000
	v_add_u32_e32 v142, s34, v196
	v_add_u32_e32 v158, s35, v196
	ds_read_b128 v[130:133], v142
	ds_read_b128 v[134:137], v142 offset:1024
	ds_read_b128 v[138:141], v142 offset:2048
	ds_read_b128 v[142:145], v142 offset:3072
	ds_read_b128 v[146:149], v158
	ds_read_b128 v[150:153], v158 offset:1024
	ds_read_b128 v[154:157], v158 offset:2048
	ds_read_b128 v[158:161], v158 offset:3072
	v_lshl_add_u64 v[194:195], s[44:45], 0, v[186:187]
	s_add_i32 m0, s93, 0xc000
	ds_read_b128 v[162:165], v201
	ds_read_b128 v[166:169], v201 offset:1024
	ds_read_b128 v[170:173], v201 offset:2048
	ds_read_b128 v[174:177], v201 offset:3072
	ds_read_b128 v[190:193], v201 offset:4096
	ds_read_b128 v[202:205], v201 offset:5120
	ds_read_b128 v[206:209], v201 offset:6144
	ds_read_b128 v[210:213], v201 offset:7168
	global_load_lds_dwordx4 v[194:195], off
	s_add_i32 m0, s93, 0xe000
	v_lshl_add_u64 v[194:195], s[44:45], 0, v[188:189]
	global_load_lds_dwordx4 v[194:195], off
	s_waitcnt vmcnt(8) lgkmcnt(0)
	s_barrier
	v_mfma_f32_16x16x32_bf16 v[126:129], v[130:133], v[162:165], v[126:129]
	v_mfma_f32_16x16x32_bf16 v[122:125], v[138:141], v[162:165], v[122:125]
	v_mfma_f32_16x16x32_bf16 v[118:121], v[130:133], v[170:173], v[118:121]
	v_mfma_f32_16x16x32_bf16 v[114:117], v[138:141], v[170:173], v[114:117]
	v_mfma_f32_16x16x32_bf16 v[110:113], v[130:133], v[190:193], v[110:113]
	v_mfma_f32_16x16x32_bf16 v[102:105], v[138:141], v[190:193], v[102:105]
	v_mfma_f32_16x16x32_bf16 v[90:93], v[130:133], v[206:209], v[90:93]
	v_mfma_f32_16x16x32_bf16 v[82:85], v[138:141], v[206:209], v[82:85]
	v_mfma_f32_16x16x32_bf16 v[126:129], v[134:137], v[166:169], v[126:129]
	v_mfma_f32_16x16x32_bf16 v[122:125], v[142:145], v[166:169], v[122:125]
	v_mfma_f32_16x16x32_bf16 v[118:121], v[134:137], v[174:177], v[118:121]
	v_mfma_f32_16x16x32_bf16 v[114:117], v[142:145], v[174:177], v[114:117]
	v_mfma_f32_16x16x32_bf16 v[110:113], v[134:137], v[202:205], v[110:113]
	v_mfma_f32_16x16x32_bf16 v[102:105], v[142:145], v[202:205], v[102:105]
	v_mfma_f32_16x16x32_bf16 v[90:93], v[134:137], v[210:213], v[90:93]
	v_mfma_f32_16x16x32_bf16 v[82:85], v[142:145], v[210:213], v[82:85]
	v_mfma_f32_16x16x32_bf16 v[106:109], v[146:149], v[162:165], v[106:109]
	v_mfma_f32_16x16x32_bf16 v[98:101], v[154:157], v[162:165], v[98:101]
	v_mfma_f32_16x16x32_bf16 v[94:97], v[146:149], v[170:173], v[94:97]
	v_mfma_f32_16x16x32_bf16 v[86:89], v[154:157], v[170:173], v[86:89]
	v_mfma_f32_16x16x32_bf16 v[70:73], v[146:149], v[190:193], v[70:73]
	v_mfma_f32_16x16x32_bf16 v[62:65], v[154:157], v[190:193], v[62:65]
	v_mfma_f32_16x16x32_bf16 v[78:81], v[146:149], v[206:209], v[78:81]
	v_mfma_f32_16x16x32_bf16 v[66:69], v[154:157], v[206:209], v[66:69]
	v_mfma_f32_16x16x32_bf16 v[106:109], v[150:153], v[166:169], v[106:109]
	v_mfma_f32_16x16x32_bf16 v[98:101], v[158:161], v[166:169], v[98:101]
	v_mfma_f32_16x16x32_bf16 v[94:97], v[150:153], v[174:177], v[94:97]
	v_mfma_f32_16x16x32_bf16 v[86:89], v[158:161], v[174:177], v[86:89]
	v_mfma_f32_16x16x32_bf16 v[70:73], v[150:153], v[202:205], v[70:73]
	v_mfma_f32_16x16x32_bf16 v[62:65], v[158:161], v[202:205], v[62:65]
	v_mfma_f32_16x16x32_bf16 v[78:81], v[150:153], v[210:213], v[78:81]
	v_mfma_f32_16x16x32_bf16 v[66:69], v[158:161], v[210:213], v[66:69]
	s_barrier
	s_add_i32 s34, s34, s91
	v_lshl_add_u64 v[194:195], s[6:7], 0, v[0:1]
	s_mov_b32 m0, s34
	ds_read_b128 v[162:165], v201 offset:16384
	ds_read_b128 v[166:169], v201 offset:17408
	ds_read_b128 v[170:173], v201 offset:18432
	ds_read_b128 v[174:177], v201 offset:19456
	ds_read_b128 v[190:193], v201 offset:20480
	ds_read_b128 v[202:205], v201 offset:21504
	ds_read_b128 v[206:209], v201 offset:22528
	ds_read_b128 v[210:213], v201 offset:23552
	global_load_lds_dwordx4 v[194:195], off
	s_add_i32 m0, s34, 0x2000
	s_add_u32 s44, s6, 0x80000
	v_lshl_add_u64 v[214:215], s[6:7], 0, v[182:183]
	s_addc_u32 s45, s7, 0
	s_add_i32 s34, s35, s91
	global_load_lds_dwordx4 v[214:215], off
	v_lshl_add_u64 v[216:217], s[44:45], 0, v[0:1]
	s_mov_b32 m0, s34
	v_lshl_add_u64 v[218:219], s[42:43], 0, v[180:181]
	global_load_lds_dwordx4 v[216:217], off
	s_add_i32 m0, s34, 0x2000
	v_lshl_add_u64 v[216:217], s[44:45], 0, v[182:183]
	global_load_lds_dwordx4 v[216:217], off
	s_mov_b32 m0, s93
	v_lshl_add_u64 v[216:217], s[42:43], 0, v[178:179]
	global_load_lds_dwordx4 v[216:217], off
	s_mov_b32 m0, s83
	s_nop 0
	global_load_lds_dwordx4 v[218:219], off
	s_waitcnt vmcnt(8) lgkmcnt(0)
	s_barrier
; #define PG8_STAGE(bufoff, gbase, voff) do { _Pragma("unroll") for (int _i = 0; _i < 2; ++_i) \
;         __builtin_amdgcn_global_load_lds((const unsigned*)((const char*)(gbase) + (voff)[_i]), (LAS unsigned*)(lds + (bufoff) + ldsw + _i * 8192), 16, 0, 0); } while (0)
; #define PG8_LDA(dst, b, h) do { _Pragma("unroll") for (int m = 0; m < 4; ++m) _Pragma("unroll") for (int k = 0; k < 2; ++k) dst[m][k] = *(const LAS bf16x8*)(lds + PG8_SA(b, h) + aoff + m * 2048 + k * 1024); } while (0)
; #define PG8_LDB(dst, b, h) do { _Pragma("unroll") for (int n = 0; n < 2; ++n) _Pragma("unroll") for (int k = 0; k < 2; ++k) dst[n][k] = *(const LAS bf16x8*)(lds + PG8_SB(b, h) + boff + n * 2048 + k * 1024); } while (0)
; #define PG8_WAIT_V(n) asm volatile("s_waitcnt vmcnt(" #n ")" ::: "memory")
; template <class Epi, int AMODE>
; __device__ __forceinline__ void gemm_phase(LAS unsigned char* lds, const Gemm g, const StaticOrder& S, const Epi& E, int stagger_us, int tid_in) {
;     ...
;         for (int t = 0; t < nt; t += 2) {
;             const bool last = (t == nt - 2);
;             const char* a1 = cA + (size_t)(t + 1) * kstep;
;             const char* a2 = last ? nA : cA + (size_t)(t + 2) * kstep; const char* b2 = last ? nB : cB + (size_t)(t + 2) * kstep;
;             const char* a3 = a2 + kstep; const char* b3 = b2 + kstep;
;             PG8_LDB(B0, 0, 0); PG8_LDB(B1, 0, 1); PG8_SCHED; PG8_LDA(At, 0, 0); PG8_STAGE(PG8_SA(1, 1), a1 + hstepA, voffA);
;             PG8_WAIT_V(8); PG8_WAIT_L(0); PG8_BAR; PG8_MMA(0, 0, At, B0); PG8_MMA(0, 1, At, B1); PG8_BAR; PG8_SCHED;
;             PG8_LDA(At, 0, 1); PG8_STAGE(PG8_SB(0, 0), b2, voffB); PG8_STAGE(PG8_SB(0, 1), b2 + hstepB, voffB); PG8_STAGE(PG8_SA(0, 0), a2, voffA);
;             PG8_WAIT_V(8); PG8_WAIT_L(0); PG8_BAR; PG8_MMA(1, 0, At, B0); PG8_MMA(1, 1, At, B1); PG8_BAR; PG8_SCHED;
;             PG8_LDB(B0, 1, 0); PG8_LDB(B1, 1, 1); PG8_SCHED; PG8_LDA(At, 1, 0); PG8_STAGE(PG8_SA(0, 1), a2 + hstepA, voffA);
;             PG8_WAIT_V(8); PG8_WAIT_L(0); PG8_BAR; PG8_MMA(0, 0, At, B0); PG8_MMA(0, 1, At, B1); PG8_BAR; PG8_SCHED;
;             PG8_LDA(At, 1, 1); PG8_STAGE(PG8_SB(1, 0), b3, voffB); PG8_STAGE(PG8_SB(1, 1), b3 + hstepB, voffB); PG8_STAGE(PG8_SA(1, 0), a3, voffA);
;             PG8_WAIT_V(8); PG8_WAIT_L(0); PG8_BAR; PG8_MMA(1, 0, At, B0); PG8_MMA(1, 1, At, B1); PG8_BAR; PG8_SCHED;
	v_mfma_f32_16x16x32_bf16 v[54:57], v[130:133], v[162:165], v[54:57]
	v_mfma_f32_16x16x32_bf16 v[46:49], v[138:141], v[162:165], v[46:49]
	v_mfma_f32_16x16x32_bf16 v[38:41], v[130:133], v[170:173], v[38:41]
	v_mfma_f32_16x16x32_bf16 v[50:53], v[138:141], v[170:173], v[50:53]
	v_mfma_f32_16x16x32_bf16 v[18:21], v[130:133], v[190:193], v[18:21]
	v_mfma_f32_16x16x32_bf16 v[34:37], v[138:141], v[190:193], v[34:37]
	v_mfma_f32_16x16x32_bf16 v[22:25], v[130:133], v[206:209], v[22:25]
	v_mfma_f32_16x16x32_bf16 v[74:77], v[138:141], v[206:209], v[74:77]
	v_mfma_f32_16x16x32_bf16 v[54:57], v[134:137], v[166:169], v[54:57]
	v_mfma_f32_16x16x32_bf16 v[46:49], v[142:145], v[166:169], v[46:49]
	v_mfma_f32_16x16x32_bf16 v[38:41], v[134:137], v[174:177], v[38:41]
	v_mfma_f32_16x16x32_bf16 v[50:53], v[142:145], v[174:177], v[50:53]
	v_mfma_f32_16x16x32_bf16 v[18:21], v[134:137], v[202:205], v[18:21]
	v_mfma_f32_16x16x32_bf16 v[34:37], v[142:145], v[202:205], v[34:37]
	v_mfma_f32_16x16x32_bf16 v[22:25], v[134:137], v[210:213], v[22:25]
	v_mfma_f32_16x16x32_bf16 v[74:77], v[142:145], v[210:213], v[74:77]
	v_mfma_f32_16x16x32_bf16 v[58:61], v[146:149], v[162:165], v[58:61]
	v_mfma_f32_16x16x32_bf16 v[30:33], v[154:157], v[162:165], v[30:33]
	v_mfma_f32_16x16x32_bf16 v[42:45], v[146:149], v[170:173], v[42:45]
	v_mfma_f32_16x16x32_bf16 v[6:9], v[154:157], v[170:173], v[6:9]
	v_mfma_f32_16x16x32_bf16 v[26:29], v[146:149], v[190:193], v[26:29]
	v_mfma_f32_16x16x32_bf16 v[10:13], v[154:157], v[190:193], v[10:13]
	v_mfma_f32_16x16x32_bf16 v[14:17], v[146:149], v[206:209], v[14:17]
	v_mfma_f32_16x16x32_bf16 v[2:5], v[154:157], v[206:209], v[2:5]
	v_mfma_f32_16x16x32_bf16 v[58:61], v[150:153], v[166:169], v[58:61]
	v_mfma_f32_16x16x32_bf16 v[30:33], v[158:161], v[166:169], v[30:33]
	v_mfma_f32_16x16x32_bf16 v[42:45], v[150:153], v[174:177], v[42:45]
	v_mfma_f32_16x16x32_bf16 v[6:9], v[158:161], v[174:177], v[6:9]
	v_mfma_f32_16x16x32_bf16 v[26:29], v[150:153], v[202:205], v[26:29]
	v_mfma_f32_16x16x32_bf16 v[10:13], v[158:161], v[202:205], v[10:13]
	v_mfma_f32_16x16x32_bf16 v[14:17], v[150:153], v[210:213], v[14:17]
	v_mfma_f32_16x16x32_bf16 v[2:5], v[158:161], v[210:213], v[2:5]
	s_barrier
	s_add_i32 s34, 0, 0x18000
	s_add_i32 s35, 0, 0x1c000
	v_add_u32_e32 v142, s34, v196
	v_add_u32_e32 v158, s35, v196
	ds_read_b128 v[130:133], v142
	ds_read_b128 v[134:137], v142 offset:1024
	ds_read_b128 v[138:141], v142 offset:2048
	ds_read_b128 v[142:145], v142 offset:3072
	ds_read_b128 v[146:149], v158
	ds_read_b128 v[150:153], v158 offset:1024
	ds_read_b128 v[154:157], v158 offset:2048
	ds_read_b128 v[158:161], v158 offset:3072
	s_add_u32 s42, s42, 0x4000
	s_addc_u32 s43, s43, 0
	s_mov_b32 m0, s79
	v_lshl_add_u64 v[220:221], s[42:43], 0, v[178:179]
	ds_read_b128 v[162:165], v201 offset:32768
	ds_read_b128 v[166:169], v201 offset:33792
	ds_read_b128 v[170:173], v201 offset:34816
	ds_read_b128 v[174:177], v201 offset:35840
	ds_read_b128 v[190:193], v201 offset:36864
	ds_read_b128 v[202:205], v201 offset:37888
	ds_read_b128 v[206:209], v201 offset:38912
	ds_read_b128 v[210:213], v201 offset:39936
	global_load_lds_dwordx4 v[220:221], off
	s_mov_b32 m0, s87
	v_lshl_add_u64 v[220:221], s[42:43], 0, v[180:181]
	global_load_lds_dwordx4 v[220:221], off
	s_waitcnt vmcnt(8) lgkmcnt(0)
	s_barrier
	v_mfma_f32_16x16x32_bf16 v[126:129], v[130:133], v[162:165], v[126:129]
	v_mfma_f32_16x16x32_bf16 v[122:125], v[138:141], v[162:165], v[122:125]
	v_mfma_f32_16x16x32_bf16 v[118:121], v[130:133], v[170:173], v[118:121]
	v_mfma_f32_16x16x32_bf16 v[114:117], v[138:141], v[170:173], v[114:117]
	v_mfma_f32_16x16x32_bf16 v[110:113], v[130:133], v[190:193], v[110:113]
	v_mfma_f32_16x16x32_bf16 v[102:105], v[138:141], v[190:193], v[102:105]
	v_mfma_f32_16x16x32_bf16 v[90:93], v[130:133], v[206:209], v[90:93]
	v_mfma_f32_16x16x32_bf16 v[82:85], v[138:141], v[206:209], v[82:85]
	v_mfma_f32_16x16x32_bf16 v[126:129], v[134:137], v[166:169], v[126:129]
	v_mfma_f32_16x16x32_bf16 v[122:125], v[142:145], v[166:169], v[122:125]
	v_mfma_f32_16x16x32_bf16 v[118:121], v[134:137], v[174:177], v[118:121]
	v_mfma_f32_16x16x32_bf16 v[114:117], v[142:145], v[174:177], v[114:117]
	v_mfma_f32_16x16x32_bf16 v[110:113], v[134:137], v[202:205], v[110:113]
	v_mfma_f32_16x16x32_bf16 v[102:105], v[142:145], v[202:205], v[102:105]
	v_mfma_f32_16x16x32_bf16 v[90:93], v[134:137], v[210:213], v[90:93]
	v_mfma_f32_16x16x32_bf16 v[82:85], v[142:145], v[210:213], v[82:85]
	v_mfma_f32_16x16x32_bf16 v[106:109], v[146:149], v[162:165], v[106:109]
	v_mfma_f32_16x16x32_bf16 v[98:101], v[154:157], v[162:165], v[98:101]
	v_mfma_f32_16x16x32_bf16 v[94:97], v[146:149], v[170:173], v[94:97]
	v_mfma_f32_16x16x32_bf16 v[86:89], v[154:157], v[170:173], v[86:89]
	v_mfma_f32_16x16x32_bf16 v[70:73], v[146:149], v[190:193], v[70:73]
	v_mfma_f32_16x16x32_bf16 v[62:65], v[154:157], v[190:193], v[62:65]
	v_mfma_f32_16x16x32_bf16 v[78:81], v[146:149], v[206:209], v[78:81]
	v_mfma_f32_16x16x32_bf16 v[66:69], v[154:157], v[206:209], v[66:69]
	v_mfma_f32_16x16x32_bf16 v[106:109], v[150:153], v[166:169], v[106:109]
	v_mfma_f32_16x16x32_bf16 v[98:101], v[158:161], v[166:169], v[98:101]
	v_mfma_f32_16x16x32_bf16 v[94:97], v[150:153], v[174:177], v[94:97]
	v_mfma_f32_16x16x32_bf16 v[86:89], v[158:161], v[174:177], v[86:89]
	v_mfma_f32_16x16x32_bf16 v[70:73], v[150:153], v[202:205], v[70:73]
	v_mfma_f32_16x16x32_bf16 v[62:65], v[158:161], v[202:205], v[62:65]
	v_mfma_f32_16x16x32_bf16 v[78:81], v[150:153], v[210:213], v[78:81]
	v_mfma_f32_16x16x32_bf16 v[66:69], v[158:161], v[210:213], v[66:69]
	s_barrier
; #define PG8_STAGE(bufoff, gbase, voff) do { _Pragma("unroll") for (int _i = 0; _i < 2; ++_i) \
;         __builtin_amdgcn_global_load_lds((const unsigned*)((const char*)(gbase) + (voff)[_i]), (LAS unsigned*)(lds + (bufoff) + ldsw + _i * 8192), 16, 0, 0); } while (0)
; #define PG8_LDA(dst, b, h) do { _Pragma("unroll") for (int m = 0; m < 4; ++m) _Pragma("unroll") for (int k = 0; k < 2; ++k) dst[m][k] = *(const LAS bf16x8*)(lds + PG8_SA(b, h) + aoff + m * 2048 + k * 1024); } while (0)
; #define PG8_LDB(dst, b, h) do { _Pragma("unroll") for (int n = 0; n < 2; ++n) _Pragma("unroll") for (int k = 0; k < 2; ++k) dst[n][k] = *(const LAS bf16x8*)(lds + PG8_SB(b, h) + boff + n * 2048 + k * 1024); } while (0)
; #define PG8_BAR __builtin_amdgcn_s_barrier()
; template <class Epi, int AMODE>
; __device__ __forceinline__ void gemm_phase(LAS unsigned char* lds, const Gemm g, const StaticOrder& S, const Epi& E, int stagger_us, int tid_in) {
;     ...
;         for (int t = 0; t < nt; t += 2) {
;             const bool last = (t == nt - 2);
;             const char* a1 = cA + (size_t)(t + 1) * kstep;
;             const char* a2 = last ? nA : cA + (size_t)(t + 2) * kstep; const char* b2 = last ? nB : cB + (size_t)(t + 2) * kstep;
;             const char* a3 = a2 + kstep; const char* b3 = b2 + kstep;
;             PG8_LDB(B0, 0, 0); PG8_LDB(B1, 0, 1); PG8_SCHED; PG8_LDA(At, 0, 0); PG8_STAGE(PG8_SA(1, 1), a1 + hstepA, voffA);
;             PG8_WAIT_V(8); PG8_WAIT_L(0); PG8_BAR; PG8_MMA(0, 0, At, B0); PG8_MMA(0, 1, At, B1); PG8_BAR; PG8_SCHED;
;             PG8_LDA(At, 0, 1); PG8_STAGE(PG8_SB(0, 0), b2, voffB); PG8_STAGE(PG8_SB(0, 1), b2 + hstepB, voffB); PG8_STAGE(PG8_SA(0, 0), a2, voffA);
;             PG8_WAIT_V(8); PG8_WAIT_L(0); PG8_BAR; PG8_MMA(1, 0, At, B0); PG8_MMA(1, 1, At, B1); PG8_BAR; PG8_SCHED;
;             PG8_LDB(B0, 1, 0); PG8_LDB(B1, 1, 1); PG8_SCHED; PG8_LDA(At, 1, 0); PG8_STAGE(PG8_SA(0, 1), a2 + hstepA, voffA);
;             PG8_WAIT_V(8); PG8_WAIT_L(0); PG8_BAR; PG8_MMA(0, 0, At, B0); PG8_MMA(0, 1, At, B1); PG8_BAR; PG8_SCHED;
;             PG8_LDA(At, 1, 1); PG8_STAGE(PG8_SB(1, 0), b3, voffB); PG8_STAGE(PG8_SB(1, 1), b3 + hstepB, voffB); PG8_STAGE(PG8_SA(1, 0), a3, voffA);
;             PG8_WAIT_V(8); PG8_WAIT_L(0); PG8_BAR; PG8_MMA(1, 0, At, B0); PG8_MMA(1, 1, At, B1); PG8_BAR; PG8_SCHED;
;         }
;         if (wr == 0) PG8_BAR;
	s_add_i32 s34, s34, s91
	v_lshl_add_u64 v[194:195], v[194:195], 0, s[74:75]
	s_mov_b32 m0, s34
	ds_read_b128 v[162:165], v201 offset:49152
	ds_read_b128 v[166:169], v201 offset:50176
	ds_read_b128 v[170:173], v201 offset:51200
	ds_read_b128 v[174:177], v201 offset:52224
	ds_read_b128 v[190:193], v201 offset:53248
	ds_read_b128 v[202:205], v201 offset:54272
	ds_read_b128 v[206:209], v201 offset:55296
	ds_read_b128 v[210:213], v201 offset:56320
	global_load_lds_dwordx4 v[194:195], off
	s_add_i32 m0, s34, 0x2000
	s_add_u32 s6, s6, 0x80080
	v_lshl_add_u64 v[194:195], v[214:215], 0, s[74:75]
	s_addc_u32 s7, s7, 0
	s_add_i32 s34, s35, s91
	global_load_lds_dwordx4 v[194:195], off
	s_mov_b32 m0, s34
	v_lshl_add_u64 v[194:195], s[6:7], 0, v[0:1]
	global_load_lds_dwordx4 v[194:195], off
	s_add_i32 m0, s34, 0x2000
	v_lshl_add_u64 v[194:195], s[6:7], 0, v[182:183]
	global_load_lds_dwordx4 v[194:195], off
	s_mov_b32 m0, s67
	v_lshl_add_u64 v[194:195], v[216:217], 0, s[74:75]
	global_load_lds_dwordx4 v[194:195], off
	s_mov_b32 m0, s85
	v_lshl_add_u64 v[194:195], v[218:219], 0, s[74:75]
	global_load_lds_dwordx4 v[194:195], off
	s_waitcnt vmcnt(8) lgkmcnt(0)
	s_barrier
	v_mfma_f32_16x16x32_bf16 v[54:57], v[130:133], v[162:165], v[54:57]
	v_mfma_f32_16x16x32_bf16 v[46:49], v[138:141], v[162:165], v[46:49]
	v_mfma_f32_16x16x32_bf16 v[38:41], v[130:133], v[170:173], v[38:41]
	v_mfma_f32_16x16x32_bf16 v[50:53], v[138:141], v[170:173], v[50:53]
	v_mfma_f32_16x16x32_bf16 v[18:21], v[130:133], v[190:193], v[18:21]
	v_mfma_f32_16x16x32_bf16 v[34:37], v[138:141], v[190:193], v[34:37]
	v_mfma_f32_16x16x32_bf16 v[22:25], v[130:133], v[206:209], v[22:25]
	v_mfma_f32_16x16x32_bf16 v[74:77], v[138:141], v[206:209], v[74:77]
	v_mfma_f32_16x16x32_bf16 v[54:57], v[134:137], v[166:169], v[54:57]
	v_mfma_f32_16x16x32_bf16 v[46:49], v[142:145], v[166:169], v[46:49]
	v_mfma_f32_16x16x32_bf16 v[38:41], v[134:137], v[174:177], v[38:41]
	v_mfma_f32_16x16x32_bf16 v[50:53], v[142:145], v[174:177], v[50:53]
	v_mfma_f32_16x16x32_bf16 v[18:21], v[134:137], v[202:205], v[18:21]
	v_mfma_f32_16x16x32_bf16 v[34:37], v[142:145], v[202:205], v[34:37]
	v_mfma_f32_16x16x32_bf16 v[22:25], v[134:137], v[210:213], v[22:25]
	v_mfma_f32_16x16x32_bf16 v[74:77], v[142:145], v[210:213], v[74:77]
	v_mfma_f32_16x16x32_bf16 v[58:61], v[146:149], v[162:165], v[58:61]
	v_mfma_f32_16x16x32_bf16 v[30:33], v[154:157], v[162:165], v[30:33]
	v_mfma_f32_16x16x32_bf16 v[42:45], v[146:149], v[170:173], v[42:45]
	v_mfma_f32_16x16x32_bf16 v[6:9], v[154:157], v[170:173], v[6:9]
	v_mfma_f32_16x16x32_bf16 v[26:29], v[146:149], v[190:193], v[26:29]
	v_mfma_f32_16x16x32_bf16 v[10:13], v[154:157], v[190:193], v[10:13]
	v_mfma_f32_16x16x32_bf16 v[14:17], v[146:149], v[206:209], v[14:17]
	v_mfma_f32_16x16x32_bf16 v[2:5], v[154:157], v[206:209], v[2:5]
	v_mfma_f32_16x16x32_bf16 v[58:61], v[150:153], v[166:169], v[58:61]
	v_mfma_f32_16x16x32_bf16 v[30:33], v[158:161], v[166:169], v[30:33]
	v_mfma_f32_16x16x32_bf16 v[42:45], v[150:153], v[174:177], v[42:45]
	v_mfma_f32_16x16x32_bf16 v[6:9], v[158:161], v[174:177], v[6:9]
	v_mfma_f32_16x16x32_bf16 v[26:29], v[150:153], v[202:205], v[26:29]
	v_mfma_f32_16x16x32_bf16 v[10:13], v[158:161], v[202:205], v[10:13]
	v_mfma_f32_16x16x32_bf16 v[14:17], v[150:153], v[210:213], v[14:17]
	v_mfma_f32_16x16x32_bf16 v[2:5], v[158:161], v[210:213], v[2:5]
	s_barrier
	s_add_i32 s31, s31, 2
	s_add_u32 s29, s29, 0x100
	s_addc_u32 s30, s30, 0
	s_cmp_gt_u32 s31, 29
	s_mov_b64 s[44:45], s[4:5]
	s_cbranch_scc0 .LBB0_1299
	s_and_b64 vcc, exec, s[48:49]
	s_cbranch_vccz .LBB0_1302
	s_barrier

; #define PG8_STAGE(bufoff, gbase, voff) do { _Pragma("unroll") for (int _i = 0; _i < 2; ++_i) \
;         __builtin_amdgcn_global_load_lds((const unsigned*)((const char*)(gbase) + (voff)[_i]), (LAS unsigned*)(lds + (bufoff) + ldsw + _i * 8192), 16, 0, 0); } while (0)
; #define PG8_LDA(dst, b, h) do { _Pragma("unroll") for (int m = 0; m < 4; ++m) _Pragma("unroll") for (int k = 0; k < 2; ++k) dst[m][k] = *(const LAS bf16x8*)(lds + PG8_SA(b, h) + aoff + m * 2048 + k * 1024); } while (0)
; #define PG8_LDB(dst, b, h) do { _Pragma("unroll") for (int n = 0; n < 2; ++n) _Pragma("unroll") for (int k = 0; k < 2; ++k) dst[n][k] = *(const LAS bf16x8*)(lds + PG8_SB(b, h) + boff + n * 2048 + k * 1024); } while (0)
; #define PG8_WAIT_V(n) asm volatile("s_waitcnt vmcnt(" #n ")" ::: "memory")
; template <class Epi, int AMODE>
; __device__ __forceinline__ void gemm_phase(LAS unsigned char* lds, const Gemm g, const StaticOrder& S, const Epi& E, int stagger_us, int tid_in) {
;     ...
;         for (int t = 0; t < nt; t += 2) {
;             const bool last = (t == nt - 2);
;             const char* a1 = cA + (size_t)(t + 1) * kstep;
;             const char* a2 = last ? nA : cA + (size_t)(t + 2) * kstep; const char* b2 = last ? nB : cB + (size_t)(t + 2) * kstep;
;             const char* a3 = a2 + kstep; const char* b3 = b2 + kstep;
;             PG8_LDB(B0, 0, 0); PG8_LDB(B1, 0, 1); PG8_SCHED; PG8_LDA(At, 0, 0); PG8_STAGE(PG8_SA(1, 1), a1 + hstepA, voffA);
;             PG8_WAIT_V(8); PG8_WAIT_L(0); PG8_BAR; PG8_MMA(0, 0, At, B0); PG8_MMA(0, 1, At, B1); PG8_BAR; PG8_SCHED;
;             PG8_LDA(At, 0, 1); PG8_STAGE(PG8_SB(0, 0), b2, voffB); PG8_STAGE(PG8_SB(0, 1), b2 + hstepB, voffB); PG8_STAGE(PG8_SA(0, 0), a2, voffA);
;             PG8_WAIT_V(8); PG8_WAIT_L(0); PG8_BAR; PG8_MMA(1, 0, At, B0); PG8_MMA(1, 1, At, B1); PG8_BAR; PG8_SCHED;
;             PG8_LDB(B0, 1, 0); PG8_LDB(B1, 1, 1); PG8_SCHED; PG8_LDA(At, 1, 0); PG8_STAGE(PG8_SA(0, 1), a2 + hstepA, voffA);
;             PG8_WAIT_V(8); PG8_WAIT_L(0); PG8_BAR; PG8_MMA(0, 0, At, B0); PG8_MMA(0, 1, At, B1); PG8_BAR; PG8_SCHED;
;             PG8_LDA(At, 1, 1); PG8_STAGE(PG8_SB(1, 0), b3, voffB); PG8_STAGE(PG8_SB(1, 1), b3 + hstepB, voffB); PG8_STAGE(PG8_SA(1, 0), a3, voffA);
;             PG8_WAIT_V(8); PG8_WAIT_L(0); PG8_BAR; PG8_MMA(1, 0, At, B0); PG8_MMA(1, 1, At, B1); PG8_BAR; PG8_SCHED;
.LBB0_1476:
	s_add_u32 s4, s54, 0x100
	s_addc_u32 s5, s55, 0
	s_add_i32 s30, 0, 0x10000
	s_cmpk_eq_i32 s29, 0x52
	s_cselect_b32 s57, s41, s5
	s_cselect_b32 s56, s40, s4
	s_cselect_b32 s7, s53, s28
	s_cselect_b32 s6, s52, s27
	s_add_i32 s34, 0, 0x14000
	v_add_u32_e32 v102, s30, v162
	v_add_u32_e32 v165, s34, v162
	ds_read_b128 v[66:69], v102
	ds_read_b128 v[70:73], v102 offset:1024
	ds_read_b128 v[74:77], v102 offset:2048
	ds_read_b128 v[102:105], v102 offset:3072
	ds_read_b128 v[152:155], v165
	ds_read_b128 v[156:159], v165 offset:1024
	ds_read_b128 v[166:169], v165 offset:2048
	ds_read_b128 v[170:173], v165 offset:3072
	v_lshl_add_u64 v[206:207], s[54:55], 0, v[148:149]
	s_add_i32 m0, s13, 0xc000
	ds_read_b128 v[174:177], v164
	ds_read_b128 v[178:181], v164 offset:1024
	ds_read_b128 v[182:185], v164 offset:2048
	ds_read_b128 v[186:189], v164 offset:3072
	ds_read_b128 v[190:193], v164 offset:4096
	ds_read_b128 v[194:197], v164 offset:5120
	ds_read_b128 v[198:201], v164 offset:6144
	ds_read_b128 v[202:205], v164 offset:7168
	global_load_lds_dwordx4 v[206:207], off
	s_add_i32 m0, s13, 0xe000
	v_lshl_add_u64 v[206:207], s[54:55], 0, v[150:151]
	global_load_lds_dwordx4 v[206:207], off
	s_waitcnt vmcnt(8) lgkmcnt(0)
	s_barrier
	v_mfma_f32_16x16x32_bf16 v[142:145], v[66:69], v[174:177], v[142:145]
	v_mfma_f32_16x16x32_bf16 v[138:141], v[74:77], v[174:177], v[138:141]
	v_mfma_f32_16x16x32_bf16 v[134:137], v[66:69], v[182:185], v[134:137]
	v_mfma_f32_16x16x32_bf16 v[130:133], v[74:77], v[182:185], v[130:133]
	v_mfma_f32_16x16x32_bf16 v[110:113], v[66:69], v[190:193], v[110:113]
	v_mfma_f32_16x16x32_bf16 v[106:109], v[74:77], v[190:193], v[106:109]
	v_mfma_f32_16x16x32_bf16 v[98:101], v[66:69], v[198:201], v[98:101]
	v_mfma_f32_16x16x32_bf16 v[94:97], v[74:77], v[198:201], v[94:97]
	v_mfma_f32_16x16x32_bf16 v[142:145], v[70:73], v[178:181], v[142:145]
	v_mfma_f32_16x16x32_bf16 v[138:141], v[102:105], v[178:181], v[138:141]
	v_mfma_f32_16x16x32_bf16 v[134:137], v[70:73], v[186:189], v[134:137]
	v_mfma_f32_16x16x32_bf16 v[130:133], v[102:105], v[186:189], v[130:133]
	v_mfma_f32_16x16x32_bf16 v[110:113], v[70:73], v[194:197], v[110:113]
	v_mfma_f32_16x16x32_bf16 v[106:109], v[102:105], v[194:197], v[106:109]
	v_mfma_f32_16x16x32_bf16 v[98:101], v[70:73], v[202:205], v[98:101]
	v_mfma_f32_16x16x32_bf16 v[94:97], v[102:105], v[202:205], v[94:97]
	v_mfma_f32_16x16x32_bf16 v[126:129], v[152:155], v[174:177], v[126:129]
	v_mfma_f32_16x16x32_bf16 v[122:125], v[166:169], v[174:177], v[122:125]
	v_mfma_f32_16x16x32_bf16 v[118:121], v[152:155], v[182:185], v[118:121]
	v_mfma_f32_16x16x32_bf16 v[114:117], v[166:169], v[182:185], v[114:117]
	v_mfma_f32_16x16x32_bf16 v[90:93], v[152:155], v[190:193], v[90:93]
	v_mfma_f32_16x16x32_bf16 v[86:89], v[166:169], v[190:193], v[86:89]
	v_mfma_f32_16x16x32_bf16 v[82:85], v[152:155], v[198:201], v[82:85]
	v_mfma_f32_16x16x32_bf16 v[78:81], v[166:169], v[198:201], v[78:81]
	v_mfma_f32_16x16x32_bf16 v[126:129], v[156:159], v[178:181], v[126:129]
	v_mfma_f32_16x16x32_bf16 v[122:125], v[170:173], v[178:181], v[122:125]
	v_mfma_f32_16x16x32_bf16 v[118:121], v[156:159], v[186:189], v[118:121]
	v_mfma_f32_16x16x32_bf16 v[114:117], v[170:173], v[186:189], v[114:117]
	v_mfma_f32_16x16x32_bf16 v[90:93], v[156:159], v[194:197], v[90:93]
	v_mfma_f32_16x16x32_bf16 v[86:89], v[170:173], v[194:197], v[86:89]
	v_mfma_f32_16x16x32_bf16 v[82:85], v[156:159], v[202:205], v[82:85]
	v_mfma_f32_16x16x32_bf16 v[78:81], v[170:173], v[202:205], v[78:81]
	s_barrier
	s_add_i32 s30, s30, s12
	v_lshl_add_u64 v[206:207], s[6:7], 0, v[0:1]
	s_mov_b32 m0, s30
	ds_read_b128 v[174:177], v164 offset:16384
	ds_read_b128 v[178:181], v164 offset:17408
	ds_read_b128 v[182:185], v164 offset:18432
	ds_read_b128 v[186:189], v164 offset:19456
	ds_read_b128 v[190:193], v164 offset:20480
	ds_read_b128 v[194:197], v164 offset:21504
	ds_read_b128 v[198:201], v164 offset:22528
	ds_read_b128 v[202:205], v164 offset:23552
	global_load_lds_dwordx4 v[206:207], off
	s_add_i32 m0, s30, 0x2000
	s_add_u32 s30, s6, 0x158000
	v_lshl_add_u64 v[208:209], s[6:7], 0, v[146:147]
	s_addc_u32 s31, s7, 0
	s_add_i32 s34, s34, s12
	global_load_lds_dwordx4 v[208:209], off
	v_lshl_add_u64 v[210:211], s[30:31], 0, v[0:1]
	s_mov_b32 m0, s34
	v_lshl_add_u64 v[212:213], s[56:57], 0, v[146:147]
	global_load_lds_dwordx4 v[210:211], off
	s_add_i32 m0, s34, 0x2000
	v_lshl_add_u64 v[210:211], s[30:31], 0, v[146:147]
	global_load_lds_dwordx4 v[210:211], off
	s_mov_b32 m0, s13
	v_lshl_add_u64 v[210:211], s[56:57], 0, v[0:1]
	global_load_lds_dwordx4 v[210:211], off
	s_mov_b32 m0, s24
	s_nop 0
	global_load_lds_dwordx4 v[212:213], off
	s_waitcnt vmcnt(8) lgkmcnt(0)
	s_barrier
; #define PG8_STAGE(bufoff, gbase, voff) do { _Pragma("unroll") for (int _i = 0; _i < 2; ++_i) \
;         __builtin_amdgcn_global_load_lds((const unsigned*)((const char*)(gbase) + (voff)[_i]), (LAS unsigned*)(lds + (bufoff) + ldsw + _i * 8192), 16, 0, 0); } while (0)
; #define PG8_LDA(dst, b, h) do { _Pragma("unroll") for (int m = 0; m < 4; ++m) _Pragma("unroll") for (int k = 0; k < 2; ++k) dst[m][k] = *(const LAS bf16x8*)(lds + PG8_SA(b, h) + aoff + m * 2048 + k * 1024); } while (0)
; #define PG8_LDB(dst, b, h) do { _Pragma("unroll") for (int n = 0; n < 2; ++n) _Pragma("unroll") for (int k = 0; k < 2; ++k) dst[n][k] = *(const LAS bf16x8*)(lds + PG8_SB(b, h) + boff + n * 2048 + k * 1024); } while (0)
; #define PG8_MMA(ai, bj, At, Bt) do { __builtin_amdgcn_s_setprio(1); _Pragma("unroll") for (int m = 0; m < 4; ++m) _Pragma("unroll") for (int n = 0; n < 2; ++n) _Pragma("unroll") for (int k = 0; k < 2; ++k) \
;         acc[ai][bj][m][n] = __builtin_amdgcn_mfma_f32_16x16x32_bf16(Bt[n][k], At[m][k], acc[ai][bj][m][n], 0, 0, 0); __builtin_amdgcn_s_setprio(0); } while (0)
; #define PG8_WAIT_V(n) asm volatile("s_waitcnt vmcnt(" #n ")" ::: "memory")
; #define PG8_WAIT_L(n) asm volatile("s_waitcnt lgkmcnt(" #n ")" ::: "memory")
; #define PG8_BAR __builtin_amdgcn_s_barrier()
; #define PG8_SCHED __builtin_amdgcn_sched_barrier(0)
; template <class Epi, int AMODE>
; __device__ __forceinline__ void gemm_phase(LAS unsigned char* lds, const Gemm g, const StaticOrder& S, const Epi& E, int stagger_us, int tid_in) {
;     ...
;             PG8_WAIT_V(8); PG8_WAIT_L(0); PG8_BAR; PG8_MMA(1, 0, At, B0); PG8_MMA(1, 1, At, B1); PG8_BAR; PG8_SCHED;
;             PG8_LDB(B0, 1, 0); PG8_LDB(B1, 1, 1); PG8_SCHED; PG8_LDA(At, 1, 0); PG8_STAGE(PG8_SA(0, 1), a2 + hstepA, voffA);
;             PG8_WAIT_V(8); PG8_WAIT_L(0); PG8_BAR; PG8_MMA(0, 0, At, B0); PG8_MMA(0, 1, At, B1); PG8_BAR; PG8_SCHED;
	v_mfma_f32_16x16x32_bf16 v[62:65], v[66:69], v[174:177], v[62:65]
	v_mfma_f32_16x16x32_bf16 v[58:61], v[74:77], v[174:177], v[58:61]
	v_mfma_f32_16x16x32_bf16 v[54:57], v[66:69], v[182:185], v[54:57]
	v_mfma_f32_16x16x32_bf16 v[50:53], v[74:77], v[182:185], v[50:53]
	v_mfma_f32_16x16x32_bf16 v[30:33], v[66:69], v[190:193], v[30:33]
	v_mfma_f32_16x16x32_bf16 v[26:29], v[74:77], v[190:193], v[26:29]
	v_mfma_f32_16x16x32_bf16 v[22:25], v[66:69], v[198:201], v[22:25]
	v_mfma_f32_16x16x32_bf16 v[10:13], v[74:77], v[198:201], v[10:13]
	v_mfma_f32_16x16x32_bf16 v[62:65], v[70:73], v[178:181], v[62:65]
	v_mfma_f32_16x16x32_bf16 v[58:61], v[102:105], v[178:181], v[58:61]
	v_mfma_f32_16x16x32_bf16 v[54:57], v[70:73], v[186:189], v[54:57]
	v_mfma_f32_16x16x32_bf16 v[50:53], v[102:105], v[186:189], v[50:53]
	v_mfma_f32_16x16x32_bf16 v[30:33], v[70:73], v[194:197], v[30:33]
	v_mfma_f32_16x16x32_bf16 v[26:29], v[102:105], v[194:197], v[26:29]
	v_mfma_f32_16x16x32_bf16 v[22:25], v[70:73], v[202:205], v[22:25]
	v_mfma_f32_16x16x32_bf16 v[10:13], v[102:105], v[202:205], v[10:13]
	v_mfma_f32_16x16x32_bf16 v[46:49], v[152:155], v[174:177], v[46:49]
	v_mfma_f32_16x16x32_bf16 v[42:45], v[166:169], v[174:177], v[42:45]
	v_mfma_f32_16x16x32_bf16 v[38:41], v[152:155], v[182:185], v[38:41]
	v_mfma_f32_16x16x32_bf16 v[34:37], v[166:169], v[182:185], v[34:37]
	v_mfma_f32_16x16x32_bf16 v[18:21], v[152:155], v[190:193], v[18:21]
	v_mfma_f32_16x16x32_bf16 v[14:17], v[166:169], v[190:193], v[14:17]
	v_mfma_f32_16x16x32_bf16 v[6:9], v[152:155], v[198:201], v[6:9]
	v_mfma_f32_16x16x32_bf16 v[2:5], v[166:169], v[198:201], v[2:5]
	v_mfma_f32_16x16x32_bf16 v[46:49], v[156:159], v[178:181], v[46:49]
	v_mfma_f32_16x16x32_bf16 v[42:45], v[170:173], v[178:181], v[42:45]
	v_mfma_f32_16x16x32_bf16 v[38:41], v[156:159], v[186:189], v[38:41]
	v_mfma_f32_16x16x32_bf16 v[34:37], v[170:173], v[186:189], v[34:37]
	v_mfma_f32_16x16x32_bf16 v[18:21], v[156:159], v[194:197], v[18:21]
	v_mfma_f32_16x16x32_bf16 v[14:17], v[170:173], v[194:197], v[14:17]
	v_mfma_f32_16x16x32_bf16 v[6:9], v[156:159], v[202:205], v[6:9]
	v_mfma_f32_16x16x32_bf16 v[2:5], v[170:173], v[202:205], v[2:5]
	s_barrier
	s_add_i32 s34, 0, 0x18000
	s_add_i32 s35, 0, 0x1c000
	v_add_u32_e32 v102, s34, v162
	v_add_u32_e32 v165, s35, v162
	ds_read_b128 v[66:69], v102
	ds_read_b128 v[70:73], v102 offset:1024
	ds_read_b128 v[74:77], v102 offset:2048
	ds_read_b128 v[102:105], v102 offset:3072
	ds_read_b128 v[152:155], v165
	ds_read_b128 v[156:159], v165 offset:1024
	ds_read_b128 v[166:169], v165 offset:2048
	ds_read_b128 v[170:173], v165 offset:3072
	s_add_u32 s30, s56, 0x158000
	s_addc_u32 s31, s57, 0
	s_mov_b32 m0, s25
	v_lshl_add_u64 v[214:215], s[30:31], 0, v[0:1]
	ds_read_b128 v[174:177], v164 offset:32768
	ds_read_b128 v[178:181], v164 offset:33792
	ds_read_b128 v[182:185], v164 offset:34816
	ds_read_b128 v[186:189], v164 offset:35840
	ds_read_b128 v[190:193], v164 offset:36864
	ds_read_b128 v[194:197], v164 offset:37888
	ds_read_b128 v[198:201], v164 offset:38912
	ds_read_b128 v[202:205], v164 offset:39936
	global_load_lds_dwordx4 v[214:215], off
	s_mov_b32 m0, s66
	v_lshl_add_u64 v[214:215], s[30:31], 0, v[146:147]
	global_load_lds_dwordx4 v[214:215], off
	s_waitcnt vmcnt(8) lgkmcnt(0)
	s_barrier
	v_mfma_f32_16x16x32_bf16 v[142:145], v[66:69], v[174:177], v[142:145]
	v_mfma_f32_16x16x32_bf16 v[138:141], v[74:77], v[174:177], v[138:141]
	v_mfma_f32_16x16x32_bf16 v[134:137], v[66:69], v[182:185], v[134:137]
	v_mfma_f32_16x16x32_bf16 v[130:133], v[74:77], v[182:185], v[130:133]
	v_mfma_f32_16x16x32_bf16 v[110:113], v[66:69], v[190:193], v[110:113]
	v_mfma_f32_16x16x32_bf16 v[106:109], v[74:77], v[190:193], v[106:109]
	v_mfma_f32_16x16x32_bf16 v[98:101], v[66:69], v[198:201], v[98:101]
	v_mfma_f32_16x16x32_bf16 v[94:97], v[74:77], v[198:201], v[94:97]
	v_mfma_f32_16x16x32_bf16 v[142:145], v[70:73], v[178:181], v[142:145]
	v_mfma_f32_16x16x32_bf16 v[138:141], v[102:105], v[178:181], v[138:141]
	v_mfma_f32_16x16x32_bf16 v[134:137], v[70:73], v[186:189], v[134:137]
	v_mfma_f32_16x16x32_bf16 v[130:133], v[102:105], v[186:189], v[130:133]
	v_mfma_f32_16x16x32_bf16 v[110:113], v[70:73], v[194:197], v[110:113]
	v_mfma_f32_16x16x32_bf16 v[106:109], v[102:105], v[194:197], v[106:109]
	v_mfma_f32_16x16x32_bf16 v[98:101], v[70:73], v[202:205], v[98:101]
	v_mfma_f32_16x16x32_bf16 v[94:97], v[102:105], v[202:205], v[94:97]
	v_mfma_f32_16x16x32_bf16 v[126:129], v[152:155], v[174:177], v[126:129]
	v_mfma_f32_16x16x32_bf16 v[122:125], v[166:169], v[174:177], v[122:125]
	v_mfma_f32_16x16x32_bf16 v[118:121], v[152:155], v[182:185], v[118:121]
	v_mfma_f32_16x16x32_bf16 v[114:117], v[166:169], v[182:185], v[114:117]
	v_mfma_f32_16x16x32_bf16 v[90:93], v[152:155], v[190:193], v[90:93]
	v_mfma_f32_16x16x32_bf16 v[86:89], v[166:169], v[190:193], v[86:89]
	v_mfma_f32_16x16x32_bf16 v[82:85], v[152:155], v[198:201], v[82:85]
	v_mfma_f32_16x16x32_bf16 v[78:81], v[166:169], v[198:201], v[78:81]
	v_mfma_f32_16x16x32_bf16 v[126:129], v[156:159], v[178:181], v[126:129]
	v_mfma_f32_16x16x32_bf16 v[122:125], v[170:173], v[178:181], v[122:125]
	v_mfma_f32_16x16x32_bf16 v[118:121], v[156:159], v[186:189], v[118:121]
	v_mfma_f32_16x16x32_bf16 v[114:117], v[170:173], v[186:189], v[114:117]
	v_mfma_f32_16x16x32_bf16 v[90:93], v[156:159], v[194:197], v[90:93]
	v_mfma_f32_16x16x32_bf16 v[86:89], v[170:173], v[194:197], v[86:89]
	v_mfma_f32_16x16x32_bf16 v[82:85], v[156:159], v[202:205], v[82:85]
	v_mfma_f32_16x16x32_bf16 v[78:81], v[170:173], v[202:205], v[78:81]
	s_barrier
; #define PG8_STAGE(bufoff, gbase, voff) do { _Pragma("unroll") for (int _i = 0; _i < 2; ++_i) \
;         __builtin_amdgcn_global_load_lds((const unsigned*)((const char*)(gbase) + (voff)[_i]), (LAS unsigned*)(lds + (bufoff) + ldsw + _i * 8192), 16, 0, 0); } while (0)
; #define PG8_LDA(dst, b, h) do { _Pragma("unroll") for (int m = 0; m < 4; ++m) _Pragma("unroll") for (int k = 0; k < 2; ++k) dst[m][k] = *(const LAS bf16x8*)(lds + PG8_SA(b, h) + aoff + m * 2048 + k * 1024); } while (0)
; #define PG8_MMA(ai, bj, At, Bt) do { __builtin_amdgcn_s_setprio(1); _Pragma("unroll") for (int m = 0; m < 4; ++m) _Pragma("unroll") for (int n = 0; n < 2; ++n) _Pragma("unroll") for (int k = 0; k < 2; ++k) \
;         acc[ai][bj][m][n] = __builtin_amdgcn_mfma_f32_16x16x32_bf16(Bt[n][k], At[m][k], acc[ai][bj][m][n], 0, 0, 0); __builtin_amdgcn_s_setprio(0); } while (0)
; #define PG8_WAIT_V(n) asm volatile("s_waitcnt vmcnt(" #n ")" ::: "memory")
; #define PG8_WAIT_L(n) asm volatile("s_waitcnt lgkmcnt(" #n ")" ::: "memory")
; #define PG8_BAR __builtin_amdgcn_s_barrier()
; #define PG8_SCHED __builtin_amdgcn_sched_barrier(0)
; template <class Epi, int AMODE>
; __device__ __forceinline__ void gemm_phase(LAS unsigned char* lds, const Gemm g, const StaticOrder& S, const Epi& E, int stagger_us, int tid_in) {
;     ...
;             PG8_LDA(At, 1, 1); PG8_STAGE(PG8_SB(1, 0), b3, voffB); PG8_STAGE(PG8_SB(1, 1), b3 + hstepB, voffB); PG8_STAGE(PG8_SA(1, 0), a3, voffA);
;             PG8_WAIT_V(8); PG8_WAIT_L(0); PG8_BAR; PG8_MMA(1, 0, At, B0); PG8_MMA(1, 1, At, B1); PG8_BAR; PG8_SCHED;
;         }
;         if (wr == 0) PG8_BAR;
	s_add_i32 s30, s34, s12
	v_lshl_add_u64 v[206:207], v[206:207], 0, s[74:75]
	s_mov_b32 m0, s30
	ds_read_b128 v[174:177], v164 offset:49152
	ds_read_b128 v[178:181], v164 offset:50176
	ds_read_b128 v[182:185], v164 offset:51200
	ds_read_b128 v[186:189], v164 offset:52224
	ds_read_b128 v[190:193], v164 offset:53248
	ds_read_b128 v[194:197], v164 offset:54272
	ds_read_b128 v[198:201], v164 offset:55296
	ds_read_b128 v[202:205], v164 offset:56320
	global_load_lds_dwordx4 v[206:207], off
	s_add_i32 m0, s30, 0x2000
	s_add_u32 s6, s6, 0x158080
	v_lshl_add_u64 v[206:207], v[208:209], 0, s[74:75]
	s_addc_u32 s7, s7, 0
	s_add_i32 s30, s35, s12
	global_load_lds_dwordx4 v[206:207], off
	s_mov_b32 m0, s30
	v_lshl_add_u64 v[206:207], s[6:7], 0, v[0:1]
	global_load_lds_dwordx4 v[206:207], off
	s_add_i32 m0, s30, 0x2000
	v_lshl_add_u64 v[206:207], s[6:7], 0, v[146:147]
	global_load_lds_dwordx4 v[206:207], off
	s_mov_b32 m0, s67
	v_lshl_add_u64 v[206:207], v[210:211], 0, s[74:75]
	global_load_lds_dwordx4 v[206:207], off
	s_mov_b32 m0, s69
	v_lshl_add_u64 v[206:207], v[212:213], 0, s[74:75]
	global_load_lds_dwordx4 v[206:207], off
	s_waitcnt vmcnt(8) lgkmcnt(0)
	s_barrier
	v_mfma_f32_16x16x32_bf16 v[62:65], v[66:69], v[174:177], v[62:65]
	v_mfma_f32_16x16x32_bf16 v[58:61], v[74:77], v[174:177], v[58:61]
	v_mfma_f32_16x16x32_bf16 v[54:57], v[66:69], v[182:185], v[54:57]
	v_mfma_f32_16x16x32_bf16 v[50:53], v[74:77], v[182:185], v[50:53]
	v_mfma_f32_16x16x32_bf16 v[30:33], v[66:69], v[190:193], v[30:33]
	v_mfma_f32_16x16x32_bf16 v[26:29], v[74:77], v[190:193], v[26:29]
	v_mfma_f32_16x16x32_bf16 v[22:25], v[66:69], v[198:201], v[22:25]
	v_mfma_f32_16x16x32_bf16 v[10:13], v[74:77], v[198:201], v[10:13]
	v_mfma_f32_16x16x32_bf16 v[62:65], v[70:73], v[178:181], v[62:65]
	v_mfma_f32_16x16x32_bf16 v[58:61], v[102:105], v[178:181], v[58:61]
	v_mfma_f32_16x16x32_bf16 v[54:57], v[70:73], v[186:189], v[54:57]
	v_mfma_f32_16x16x32_bf16 v[50:53], v[102:105], v[186:189], v[50:53]
	v_mfma_f32_16x16x32_bf16 v[30:33], v[70:73], v[194:197], v[30:33]
	v_mfma_f32_16x16x32_bf16 v[26:29], v[102:105], v[194:197], v[26:29]
	v_mfma_f32_16x16x32_bf16 v[22:25], v[70:73], v[202:205], v[22:25]
	v_mfma_f32_16x16x32_bf16 v[10:13], v[102:105], v[202:205], v[10:13]
	v_mfma_f32_16x16x32_bf16 v[46:49], v[152:155], v[174:177], v[46:49]
	v_mfma_f32_16x16x32_bf16 v[42:45], v[166:169], v[174:177], v[42:45]
	v_mfma_f32_16x16x32_bf16 v[38:41], v[152:155], v[182:185], v[38:41]
	v_mfma_f32_16x16x32_bf16 v[34:37], v[166:169], v[182:185], v[34:37]
	v_mfma_f32_16x16x32_bf16 v[18:21], v[152:155], v[190:193], v[18:21]
	v_mfma_f32_16x16x32_bf16 v[14:17], v[166:169], v[190:193], v[14:17]
	v_mfma_f32_16x16x32_bf16 v[6:9], v[152:155], v[198:201], v[6:9]
	v_mfma_f32_16x16x32_bf16 v[2:5], v[166:169], v[198:201], v[2:5]
	v_mfma_f32_16x16x32_bf16 v[46:49], v[156:159], v[178:181], v[46:49]
	v_mfma_f32_16x16x32_bf16 v[42:45], v[170:173], v[178:181], v[42:45]
	v_mfma_f32_16x16x32_bf16 v[38:41], v[156:159], v[186:189], v[38:41]
	v_mfma_f32_16x16x32_bf16 v[34:37], v[170:173], v[186:189], v[34:37]
	v_mfma_f32_16x16x32_bf16 v[18:21], v[156:159], v[194:197], v[18:21]
	v_mfma_f32_16x16x32_bf16 v[14:17], v[170:173], v[194:197], v[14:17]
	v_mfma_f32_16x16x32_bf16 v[6:9], v[156:159], v[202:205], v[6:9]
	v_mfma_f32_16x16x32_bf16 v[2:5], v[170:173], v[202:205], v[2:5]
	s_barrier
	s_add_i32 s29, s29, 2
	s_add_u32 s27, s27, 0x100
	s_addc_u32 s28, s28, 0
	s_cmpk_gt_u32 s29, 0x53
	s_mov_b64 s[54:55], s[4:5]
	s_cbranch_scc0 .LBB0_1476
	s_and_b64 vcc, exec, s[46:47]
	s_cbranch_vccz .LBB0_1479
	s_barrier

; #define PG8_STAGE(bufoff, gbase, voff) do { _Pragma("unroll") for (int _i = 0; _i < 2; ++_i) \
;         __builtin_amdgcn_global_load_lds((const unsigned*)((const char*)(gbase) + (voff)[_i]), (LAS unsigned*)(lds + (bufoff) + ldsw + _i * 8192), 16, 0, 0); } while (0)
; #define PG8_LDA(dst, b, h) do { _Pragma("unroll") for (int m = 0; m < 4; ++m) _Pragma("unroll") for (int k = 0; k < 2; ++k) dst[m][k] = *(const LAS bf16x8*)(lds + PG8_SA(b, h) + aoff + m * 2048 + k * 1024); } while (0)
; #define PG8_LDB(dst, b, h) do { _Pragma("unroll") for (int n = 0; n < 2; ++n) _Pragma("unroll") for (int k = 0; k < 2; ++k) dst[n][k] = *(const LAS bf16x8*)(lds + PG8_SB(b, h) + boff + n * 2048 + k * 1024); } while (0)
; #define PG8_MMA(ai, bj, At, Bt) do { __builtin_amdgcn_s_setprio(1); _Pragma("unroll") for (int m = 0; m < 4; ++m) _Pragma("unroll") for (int n = 0; n < 2; ++n) _Pragma("unroll") for (int k = 0; k < 2; ++k) \
;         acc[ai][bj][m][n] = __builtin_amdgcn_mfma_f32_16x16x32_bf16(Bt[n][k], At[m][k], acc[ai][bj][m][n], 0, 0, 0); __builtin_amdgcn_s_setprio(0); } while (0)
; #define PG8_WAIT_V(n) asm volatile("s_waitcnt vmcnt(" #n ")" ::: "memory")
; #define PG8_WAIT_L(n) asm volatile("s_waitcnt lgkmcnt(" #n ")" ::: "memory")
; #define PG8_BAR __builtin_amdgcn_s_barrier()
; #define PG8_SCHED __builtin_amdgcn_sched_barrier(0)
; template <class Epi, int AMODE>
; __device__ __forceinline__ void gemm_phase(LAS unsigned char* lds, const Gemm g, const StaticOrder& S, const Epi& E, int stagger_us, int tid_in) {
;     ...
;             const bool last = (t == nt - 2);
;             const char* a1 = cA + (size_t)(t + 1) * kstep;
;             const char* a2 = last ? nA : cA + (size_t)(t + 2) * kstep; const char* b2 = last ? nB : cB + (size_t)(t + 2) * kstep;
;             const char* a3 = a2 + kstep; const char* b3 = b2 + kstep;
;             PG8_LDB(B0, 0, 0); PG8_LDB(B1, 0, 1); PG8_SCHED; PG8_LDA(At, 0, 0); PG8_STAGE(PG8_SA(1, 1), a1 + hstepA, voffA);
;             PG8_WAIT_V(8); PG8_WAIT_L(0); PG8_BAR; PG8_MMA(0, 0, At, B0); PG8_MMA(0, 1, At, B1); PG8_BAR; PG8_SCHED;
;             PG8_LDA(At, 0, 1); PG8_STAGE(PG8_SB(0, 0), b2, voffB); PG8_STAGE(PG8_SB(0, 1), b2 + hstepB, voffB); PG8_STAGE(PG8_SA(0, 0), a2, voffA);
.LBB0_1498:
	s_add_u32 s4, s46, 0x100
	s_addc_u32 s5, s47, 0
	s_add_i32 s30, 0, 0x10000
	s_cmpk_eq_i32 s29, 0x52
	s_cselect_b32 s59, s41, s5
	s_cselect_b32 s58, s40, s4
	s_cselect_b32 s7, s57, s28
	s_cselect_b32 s6, s56, s27
	s_add_i32 s34, 0, 0x14000
	v_add_u32_e32 v62, s30, v209
	v_add_u32_e32 v158, s34, v209
	ds_read_b128 v[50:53], v62
	ds_read_b128 v[54:57], v62 offset:1024
	ds_read_b128 v[58:61], v62 offset:2048
	ds_read_b128 v[62:65], v62 offset:3072
	ds_read_b128 v[146:149], v158
	ds_read_b128 v[150:153], v158 offset:1024
	ds_read_b128 v[154:157], v158 offset:2048
	ds_read_b128 v[158:161], v158 offset:3072
	v_lshl_add_u64 v[200:201], s[46:47], 0, v[176:177]
	s_add_i32 m0, s13, 0xc000
	ds_read_b128 v[162:165], v215
	ds_read_b128 v[166:169], v215 offset:1024
	ds_read_b128 v[170:173], v215 offset:2048
	ds_read_b128 v[180:183], v215 offset:3072
	ds_read_b128 v[184:187], v215 offset:4096
	ds_read_b128 v[188:191], v215 offset:5120
	ds_read_b128 v[192:195], v215 offset:6144
	ds_read_b128 v[196:199], v215 offset:7168
	global_load_lds_dwordx4 v[200:201], off
	s_add_i32 m0, s13, 0xe000
	v_lshl_add_u64 v[200:201], s[46:47], 0, v[178:179]
	global_load_lds_dwordx4 v[200:201], off
	s_waitcnt vmcnt(8) lgkmcnt(0)
	s_barrier
	v_mfma_f32_16x16x32_bf16 v[142:145], v[50:53], v[162:165], v[142:145]
	v_mfma_f32_16x16x32_bf16 v[138:141], v[58:61], v[162:165], v[138:141]
	v_mfma_f32_16x16x32_bf16 v[126:129], v[50:53], v[170:173], v[126:129]
	v_mfma_f32_16x16x32_bf16 v[122:125], v[58:61], v[170:173], v[122:125]
	v_mfma_f32_16x16x32_bf16 v[110:113], v[50:53], v[184:187], v[110:113]
	v_mfma_f32_16x16x32_bf16 v[106:109], v[58:61], v[184:187], v[106:109]
	v_mfma_f32_16x16x32_bf16 v[94:97], v[50:53], v[192:195], v[94:97]
	v_mfma_f32_16x16x32_bf16 v[90:93], v[58:61], v[192:195], v[90:93]
	v_mfma_f32_16x16x32_bf16 v[142:145], v[54:57], v[166:169], v[142:145]
	v_mfma_f32_16x16x32_bf16 v[138:141], v[62:65], v[166:169], v[138:141]
	v_mfma_f32_16x16x32_bf16 v[126:129], v[54:57], v[180:183], v[126:129]
	v_mfma_f32_16x16x32_bf16 v[122:125], v[62:65], v[180:183], v[122:125]
	v_mfma_f32_16x16x32_bf16 v[110:113], v[54:57], v[188:191], v[110:113]
	v_mfma_f32_16x16x32_bf16 v[106:109], v[62:65], v[188:191], v[106:109]
	v_mfma_f32_16x16x32_bf16 v[94:97], v[54:57], v[196:199], v[94:97]
	v_mfma_f32_16x16x32_bf16 v[90:93], v[62:65], v[196:199], v[90:93]
	v_mfma_f32_16x16x32_bf16 v[134:137], v[146:149], v[162:165], v[134:137]
	v_mfma_f32_16x16x32_bf16 v[130:133], v[154:157], v[162:165], v[130:133]
	v_mfma_f32_16x16x32_bf16 v[118:121], v[146:149], v[170:173], v[118:121]
	v_mfma_f32_16x16x32_bf16 v[114:117], v[154:157], v[170:173], v[114:117]
	v_mfma_f32_16x16x32_bf16 v[102:105], v[146:149], v[184:187], v[102:105]
	v_mfma_f32_16x16x32_bf16 v[98:101], v[154:157], v[184:187], v[98:101]
	v_mfma_f32_16x16x32_bf16 v[86:89], v[146:149], v[192:195], v[86:89]
	v_mfma_f32_16x16x32_bf16 v[82:85], v[154:157], v[192:195], v[82:85]
	v_mfma_f32_16x16x32_bf16 v[134:137], v[150:153], v[166:169], v[134:137]
	v_mfma_f32_16x16x32_bf16 v[130:133], v[158:161], v[166:169], v[130:133]
	v_mfma_f32_16x16x32_bf16 v[118:121], v[150:153], v[180:183], v[118:121]
	v_mfma_f32_16x16x32_bf16 v[114:117], v[158:161], v[180:183], v[114:117]
	v_mfma_f32_16x16x32_bf16 v[102:105], v[150:153], v[188:191], v[102:105]
	v_mfma_f32_16x16x32_bf16 v[98:101], v[158:161], v[188:191], v[98:101]
	v_mfma_f32_16x16x32_bf16 v[86:89], v[150:153], v[196:199], v[86:89]
	v_mfma_f32_16x16x32_bf16 v[82:85], v[158:161], v[196:199], v[82:85]
	s_barrier
	s_add_i32 s30, s30, s12
	v_lshl_add_u64 v[200:201], s[6:7], 0, v[0:1]
	s_mov_b32 m0, s30
	ds_read_b128 v[162:165], v215 offset:16384
	ds_read_b128 v[166:169], v215 offset:17408
	ds_read_b128 v[170:173], v215 offset:18432
	ds_read_b128 v[180:183], v215 offset:19456
	ds_read_b128 v[184:187], v215 offset:20480
	ds_read_b128 v[188:191], v215 offset:21504
	ds_read_b128 v[192:195], v215 offset:22528
	ds_read_b128 v[196:199], v215 offset:23552
	global_load_lds_dwordx4 v[200:201], off
	s_add_i32 m0, s30, 0x2000
	s_add_u32 s30, s6, 0x158000
	v_lshl_add_u64 v[202:203], s[6:7], 0, v[174:175]
	s_addc_u32 s31, s7, 0
	s_add_i32 s34, s34, s12
	global_load_lds_dwordx4 v[202:203], off
	v_lshl_add_u64 v[204:205], s[30:31], 0, v[0:1]
	s_mov_b32 m0, s34
	v_lshl_add_u64 v[206:207], s[58:59], 0, v[174:175]
	global_load_lds_dwordx4 v[204:205], off
	s_add_i32 m0, s34, 0x2000
	v_lshl_add_u64 v[204:205], s[30:31], 0, v[174:175]
	global_load_lds_dwordx4 v[204:205], off
	s_mov_b32 m0, s13
	v_lshl_add_u64 v[204:205], s[58:59], 0, v[0:1]
	global_load_lds_dwordx4 v[204:205], off
	s_mov_b32 m0, s24
	s_nop 0
	global_load_lds_dwordx4 v[206:207], off
	s_waitcnt vmcnt(8) lgkmcnt(0)
	s_barrier
; #define PG8_STAGE(bufoff, gbase, voff) do { _Pragma("unroll") for (int _i = 0; _i < 2; ++_i) \
;         __builtin_amdgcn_global_load_lds((const unsigned*)((const char*)(gbase) + (voff)[_i]), (LAS unsigned*)(lds + (bufoff) + ldsw + _i * 8192), 16, 0, 0); } while (0)
; #define PG8_LDA(dst, b, h) do { _Pragma("unroll") for (int m = 0; m < 4; ++m) _Pragma("unroll") for (int k = 0; k < 2; ++k) dst[m][k] = *(const LAS bf16x8*)(lds + PG8_SA(b, h) + aoff + m * 2048 + k * 1024); } while (0)
; #define PG8_LDB(dst, b, h) do { _Pragma("unroll") for (int n = 0; n < 2; ++n) _Pragma("unroll") for (int k = 0; k < 2; ++k) dst[n][k] = *(const LAS bf16x8*)(lds + PG8_SB(b, h) + boff + n * 2048 + k * 1024); } while (0)
; #define PG8_MMA(ai, bj, At, Bt) do { __builtin_amdgcn_s_setprio(1); _Pragma("unroll") for (int m = 0; m < 4; ++m) _Pragma("unroll") for (int n = 0; n < 2; ++n) _Pragma("unroll") for (int k = 0; k < 2; ++k) \
;         acc[ai][bj][m][n] = __builtin_amdgcn_mfma_f32_16x16x32_bf16(Bt[n][k], At[m][k], acc[ai][bj][m][n], 0, 0, 0); __builtin_amdgcn_s_setprio(0); } while (0)
; #define PG8_WAIT_V(n) asm volatile("s_waitcnt vmcnt(" #n ")" ::: "memory")
; #define PG8_WAIT_L(n) asm volatile("s_waitcnt lgkmcnt(" #n ")" ::: "memory")
; #define PG8_BAR __builtin_amdgcn_s_barrier()
; #define PG8_SCHED __builtin_amdgcn_sched_barrier(0)
; template <class Epi, int AMODE>
; __device__ __forceinline__ void gemm_phase(LAS unsigned char* lds, const Gemm g, const StaticOrder& S, const Epi& E, int stagger_us, int tid_in) {
;     ...
;             PG8_WAIT_V(8); PG8_WAIT_L(0); PG8_BAR; PG8_MMA(1, 0, At, B0); PG8_MMA(1, 1, At, B1); PG8_BAR; PG8_SCHED;
;             PG8_LDB(B0, 1, 0); PG8_LDB(B1, 1, 1); PG8_SCHED; PG8_LDA(At, 1, 0); PG8_STAGE(PG8_SA(0, 1), a2 + hstepA, voffA);
;             PG8_WAIT_V(8); PG8_WAIT_L(0); PG8_BAR; PG8_MMA(0, 0, At, B0); PG8_MMA(0, 1, At, B1); PG8_BAR; PG8_SCHED;
	v_mfma_f32_16x16x32_bf16 v[78:81], v[50:53], v[162:165], v[78:81]
	v_mfma_f32_16x16x32_bf16 v[74:77], v[58:61], v[162:165], v[74:77]
	v_mfma_f32_16x16x32_bf16 v[46:49], v[50:53], v[170:173], v[46:49]
	v_mfma_f32_16x16x32_bf16 v[42:45], v[58:61], v[170:173], v[42:45]
	v_mfma_f32_16x16x32_bf16 v[30:33], v[50:53], v[184:187], v[30:33]
	v_mfma_f32_16x16x32_bf16 v[26:29], v[58:61], v[184:187], v[26:29]
	v_mfma_f32_16x16x32_bf16 v[14:17], v[50:53], v[192:195], v[14:17]
	v_mfma_f32_16x16x32_bf16 v[10:13], v[58:61], v[192:195], v[10:13]
	v_mfma_f32_16x16x32_bf16 v[78:81], v[54:57], v[166:169], v[78:81]
	v_mfma_f32_16x16x32_bf16 v[74:77], v[62:65], v[166:169], v[74:77]
	v_mfma_f32_16x16x32_bf16 v[46:49], v[54:57], v[180:183], v[46:49]
	v_mfma_f32_16x16x32_bf16 v[42:45], v[62:65], v[180:183], v[42:45]
	v_mfma_f32_16x16x32_bf16 v[30:33], v[54:57], v[188:191], v[30:33]
	v_mfma_f32_16x16x32_bf16 v[26:29], v[62:65], v[188:191], v[26:29]
	v_mfma_f32_16x16x32_bf16 v[14:17], v[54:57], v[196:199], v[14:17]
	v_mfma_f32_16x16x32_bf16 v[10:13], v[62:65], v[196:199], v[10:13]
	v_mfma_f32_16x16x32_bf16 v[38:41], v[146:149], v[170:173], v[38:41]
	v_mfma_f32_16x16x32_bf16 v[34:37], v[154:157], v[170:173], v[34:37]
	v_mfma_f32_16x16x32_bf16 v[22:25], v[146:149], v[184:187], v[22:25]
	v_mfma_f32_16x16x32_bf16 v[18:21], v[154:157], v[184:187], v[18:21]
	v_mfma_f32_16x16x32_bf16 v[6:9], v[146:149], v[192:195], v[6:9]
	v_mfma_f32_16x16x32_bf16 v[2:5], v[154:157], v[192:195], v[2:5]
	v_mfma_f32_16x16x32_bf16 v[50:53], v[146:149], v[162:165], v[70:73]
	v_mfma_f32_16x16x32_bf16 v[54:57], v[154:157], v[162:165], v[66:69]
	v_mfma_f32_16x16x32_bf16 v[38:41], v[150:153], v[180:183], v[38:41]
	v_mfma_f32_16x16x32_bf16 v[34:37], v[158:161], v[180:183], v[34:37]
	v_mfma_f32_16x16x32_bf16 v[22:25], v[150:153], v[188:191], v[22:25]
	v_mfma_f32_16x16x32_bf16 v[18:21], v[158:161], v[188:191], v[18:21]
	v_mfma_f32_16x16x32_bf16 v[6:9], v[150:153], v[196:199], v[6:9]
	v_mfma_f32_16x16x32_bf16 v[2:5], v[158:161], v[196:199], v[2:5]
	v_mfma_f32_16x16x32_bf16 v[50:53], v[150:153], v[166:169], v[50:53]
	v_mfma_f32_16x16x32_bf16 v[54:57], v[158:161], v[166:169], v[54:57]
	s_barrier
	s_add_i32 s34, 0, 0x18000
	s_add_i32 s35, 0, 0x1c000
	v_add_u32_e32 v70, s34, v209
	v_add_u32_e32 v158, s35, v209
	ds_read_b128 v[58:61], v70
	ds_read_b128 v[62:65], v70 offset:1024
	ds_read_b128 v[66:69], v70 offset:2048
	ds_read_b128 v[70:73], v70 offset:3072
	ds_read_b128 v[146:149], v158
	ds_read_b128 v[150:153], v158 offset:1024
	ds_read_b128 v[154:157], v158 offset:2048
	ds_read_b128 v[158:161], v158 offset:3072
	s_add_u32 s30, s58, 0x158000
	s_addc_u32 s31, s59, 0
	s_mov_b32 m0, s25
	v_lshl_add_u64 v[210:211], s[30:31], 0, v[0:1]
	ds_read_b128 v[162:165], v215 offset:32768
	ds_read_b128 v[166:169], v215 offset:33792
	ds_read_b128 v[170:173], v215 offset:34816
	ds_read_b128 v[180:183], v215 offset:35840
	ds_read_b128 v[184:187], v215 offset:36864
	ds_read_b128 v[188:191], v215 offset:37888
	ds_read_b128 v[192:195], v215 offset:38912
	ds_read_b128 v[196:199], v215 offset:39936
	global_load_lds_dwordx4 v[210:211], off
	s_mov_b32 m0, s66
	v_lshl_add_u64 v[210:211], s[30:31], 0, v[174:175]
	global_load_lds_dwordx4 v[210:211], off
	s_waitcnt vmcnt(8) lgkmcnt(0)
	s_barrier
	v_mfma_f32_16x16x32_bf16 v[142:145], v[58:61], v[162:165], v[142:145]
	v_mfma_f32_16x16x32_bf16 v[138:141], v[66:69], v[162:165], v[138:141]
	v_mfma_f32_16x16x32_bf16 v[126:129], v[58:61], v[170:173], v[126:129]
	v_mfma_f32_16x16x32_bf16 v[122:125], v[66:69], v[170:173], v[122:125]
	v_mfma_f32_16x16x32_bf16 v[110:113], v[58:61], v[184:187], v[110:113]
	v_mfma_f32_16x16x32_bf16 v[106:109], v[66:69], v[184:187], v[106:109]
	v_mfma_f32_16x16x32_bf16 v[94:97], v[58:61], v[192:195], v[94:97]
	v_mfma_f32_16x16x32_bf16 v[90:93], v[66:69], v[192:195], v[90:93]
	v_mfma_f32_16x16x32_bf16 v[142:145], v[62:65], v[166:169], v[142:145]
	v_mfma_f32_16x16x32_bf16 v[138:141], v[70:73], v[166:169], v[138:141]
	v_mfma_f32_16x16x32_bf16 v[126:129], v[62:65], v[180:183], v[126:129]
	v_mfma_f32_16x16x32_bf16 v[122:125], v[70:73], v[180:183], v[122:125]
	v_mfma_f32_16x16x32_bf16 v[110:113], v[62:65], v[188:191], v[110:113]
	v_mfma_f32_16x16x32_bf16 v[106:109], v[70:73], v[188:191], v[106:109]
	v_mfma_f32_16x16x32_bf16 v[94:97], v[62:65], v[196:199], v[94:97]
	v_mfma_f32_16x16x32_bf16 v[90:93], v[70:73], v[196:199], v[90:93]
	v_mfma_f32_16x16x32_bf16 v[134:137], v[146:149], v[162:165], v[134:137]
	v_mfma_f32_16x16x32_bf16 v[130:133], v[154:157], v[162:165], v[130:133]
	v_mfma_f32_16x16x32_bf16 v[118:121], v[146:149], v[170:173], v[118:121]
	v_mfma_f32_16x16x32_bf16 v[114:117], v[154:157], v[170:173], v[114:117]
	v_mfma_f32_16x16x32_bf16 v[102:105], v[146:149], v[184:187], v[102:105]
	v_mfma_f32_16x16x32_bf16 v[98:101], v[154:157], v[184:187], v[98:101]
	v_mfma_f32_16x16x32_bf16 v[86:89], v[146:149], v[192:195], v[86:89]
	v_mfma_f32_16x16x32_bf16 v[82:85], v[154:157], v[192:195], v[82:85]
	v_mfma_f32_16x16x32_bf16 v[134:137], v[150:153], v[166:169], v[134:137]
	v_mfma_f32_16x16x32_bf16 v[130:133], v[158:161], v[166:169], v[130:133]
	v_mfma_f32_16x16x32_bf16 v[118:121], v[150:153], v[180:183], v[118:121]
	v_mfma_f32_16x16x32_bf16 v[114:117], v[158:161], v[180:183], v[114:117]
	v_mfma_f32_16x16x32_bf16 v[102:105], v[150:153], v[188:191], v[102:105]
	v_mfma_f32_16x16x32_bf16 v[98:101], v[158:161], v[188:191], v[98:101]
	v_mfma_f32_16x16x32_bf16 v[86:89], v[150:153], v[196:199], v[86:89]
	v_mfma_f32_16x16x32_bf16 v[82:85], v[158:161], v[196:199], v[82:85]
	s_barrier
; #define PG8_STAGE(bufoff, gbase, voff) do { _Pragma("unroll") for (int _i = 0; _i < 2; ++_i) \
;         __builtin_amdgcn_global_load_lds((const unsigned*)((const char*)(gbase) + (voff)[_i]), (LAS unsigned*)(lds + (bufoff) + ldsw + _i * 8192), 16, 0, 0); } while (0)
; #define PG8_LDA(dst, b, h) do { _Pragma("unroll") for (int m = 0; m < 4; ++m) _Pragma("unroll") for (int k = 0; k < 2; ++k) dst[m][k] = *(const LAS bf16x8*)(lds + PG8_SA(b, h) + aoff + m * 2048 + k * 1024); } while (0)
; #define PG8_MMA(ai, bj, At, Bt) do { __builtin_amdgcn_s_setprio(1); _Pragma("unroll") for (int m = 0; m < 4; ++m) _Pragma("unroll") for (int n = 0; n < 2; ++n) _Pragma("unroll") for (int k = 0; k < 2; ++k) \
;         acc[ai][bj][m][n] = __builtin_amdgcn_mfma_f32_16x16x32_bf16(Bt[n][k], At[m][k], acc[ai][bj][m][n], 0, 0, 0); __builtin_amdgcn_s_setprio(0); } while (0)
; #define PG8_WAIT_V(n) asm volatile("s_waitcnt vmcnt(" #n ")" ::: "memory")
; #define PG8_WAIT_L(n) asm volatile("s_waitcnt lgkmcnt(" #n ")" ::: "memory")
; #define PG8_BAR __builtin_amdgcn_s_barrier()
; #define PG8_SCHED __builtin_amdgcn_sched_barrier(0)
; template <class Epi, int AMODE>
; __device__ __forceinline__ void gemm_phase(LAS unsigned char* lds, const Gemm g, const StaticOrder& S, const Epi& E, int stagger_us, int tid_in) {
;     ...
;             PG8_LDA(At, 1, 1); PG8_STAGE(PG8_SB(1, 0), b3, voffB); PG8_STAGE(PG8_SB(1, 1), b3 + hstepB, voffB); PG8_STAGE(PG8_SA(1, 0), a3, voffA);
;             PG8_WAIT_V(8); PG8_WAIT_L(0); PG8_BAR; PG8_MMA(1, 0, At, B0); PG8_MMA(1, 1, At, B1); PG8_BAR; PG8_SCHED;
;         }
;         if (wr == 0) PG8_BAR;
	s_add_i32 s30, s34, s12
	v_lshl_add_u64 v[200:201], v[200:201], 0, s[74:75]
	s_mov_b32 m0, s30
	ds_read_b128 v[162:165], v215 offset:49152
	ds_read_b128 v[166:169], v215 offset:50176
	ds_read_b128 v[170:173], v215 offset:51200
	ds_read_b128 v[180:183], v215 offset:52224
	ds_read_b128 v[184:187], v215 offset:53248
	ds_read_b128 v[188:191], v215 offset:54272
	ds_read_b128 v[192:195], v215 offset:55296
	ds_read_b128 v[196:199], v215 offset:56320
	global_load_lds_dwordx4 v[200:201], off
	s_add_i32 m0, s30, 0x2000
	s_add_u32 s6, s6, 0x158080
	v_lshl_add_u64 v[200:201], v[202:203], 0, s[74:75]
	s_addc_u32 s7, s7, 0
	s_add_i32 s30, s35, s12
	global_load_lds_dwordx4 v[200:201], off
	s_mov_b32 m0, s30
	v_lshl_add_u64 v[200:201], s[6:7], 0, v[0:1]
	global_load_lds_dwordx4 v[200:201], off
	s_add_i32 m0, s30, 0x2000
	v_lshl_add_u64 v[200:201], s[6:7], 0, v[174:175]
	global_load_lds_dwordx4 v[200:201], off
	s_mov_b32 m0, s79
	v_lshl_add_u64 v[200:201], v[204:205], 0, s[74:75]
	global_load_lds_dwordx4 v[200:201], off
	s_mov_b32 m0, s83
	v_lshl_add_u64 v[200:201], v[206:207], 0, s[74:75]
	global_load_lds_dwordx4 v[200:201], off
	s_waitcnt vmcnt(8) lgkmcnt(0)
	s_barrier
	v_mfma_f32_16x16x32_bf16 v[78:81], v[58:61], v[162:165], v[78:81]
	v_mfma_f32_16x16x32_bf16 v[74:77], v[66:69], v[162:165], v[74:77]
	v_mfma_f32_16x16x32_bf16 v[46:49], v[58:61], v[170:173], v[46:49]
	v_mfma_f32_16x16x32_bf16 v[42:45], v[66:69], v[170:173], v[42:45]
	v_mfma_f32_16x16x32_bf16 v[30:33], v[58:61], v[184:187], v[30:33]
	v_mfma_f32_16x16x32_bf16 v[26:29], v[66:69], v[184:187], v[26:29]
	v_mfma_f32_16x16x32_bf16 v[14:17], v[58:61], v[192:195], v[14:17]
	v_mfma_f32_16x16x32_bf16 v[10:13], v[66:69], v[192:195], v[10:13]
	v_mfma_f32_16x16x32_bf16 v[78:81], v[62:65], v[166:169], v[78:81]
	v_mfma_f32_16x16x32_bf16 v[74:77], v[70:73], v[166:169], v[74:77]
	v_mfma_f32_16x16x32_bf16 v[46:49], v[62:65], v[180:183], v[46:49]
	v_mfma_f32_16x16x32_bf16 v[42:45], v[70:73], v[180:183], v[42:45]
	v_mfma_f32_16x16x32_bf16 v[30:33], v[62:65], v[188:191], v[30:33]
	v_mfma_f32_16x16x32_bf16 v[26:29], v[70:73], v[188:191], v[26:29]
	v_mfma_f32_16x16x32_bf16 v[14:17], v[62:65], v[196:199], v[14:17]
	v_mfma_f32_16x16x32_bf16 v[10:13], v[70:73], v[196:199], v[10:13]
	v_mfma_f32_16x16x32_bf16 v[50:53], v[146:149], v[162:165], v[50:53]
	v_mfma_f32_16x16x32_bf16 v[70:73], v[150:153], v[166:169], v[50:53]
	v_mfma_f32_16x16x32_bf16 v[50:53], v[154:157], v[162:165], v[54:57]
	v_mfma_f32_16x16x32_bf16 v[38:41], v[146:149], v[170:173], v[38:41]
	v_mfma_f32_16x16x32_bf16 v[34:37], v[154:157], v[170:173], v[34:37]
	v_mfma_f32_16x16x32_bf16 v[22:25], v[146:149], v[184:187], v[22:25]
	v_mfma_f32_16x16x32_bf16 v[18:21], v[154:157], v[184:187], v[18:21]
	v_mfma_f32_16x16x32_bf16 v[6:9], v[146:149], v[192:195], v[6:9]
	v_mfma_f32_16x16x32_bf16 v[2:5], v[154:157], v[192:195], v[2:5]
	v_mfma_f32_16x16x32_bf16 v[66:69], v[158:161], v[166:169], v[50:53]
	v_mfma_f32_16x16x32_bf16 v[38:41], v[150:153], v[180:183], v[38:41]
	v_mfma_f32_16x16x32_bf16 v[34:37], v[158:161], v[180:183], v[34:37]
	v_mfma_f32_16x16x32_bf16 v[22:25], v[150:153], v[188:191], v[22:25]
	v_mfma_f32_16x16x32_bf16 v[18:21], v[158:161], v[188:191], v[18:21]
	v_mfma_f32_16x16x32_bf16 v[6:9], v[150:153], v[196:199], v[6:9]
	v_mfma_f32_16x16x32_bf16 v[2:5], v[158:161], v[196:199], v[2:5]
	s_barrier
	s_add_i32 s29, s29, 2
	s_add_u32 s27, s27, 0x100
	s_addc_u32 s28, s28, 0
	s_cmpk_gt_u32 s29, 0x53
	s_mov_b64 s[46:47], s[4:5]
	s_cbranch_scc0 .LBB0_1498
	s_and_b64 vcc, exec, s[54:55]
	s_cbranch_vccz .LBB0_1501
	s_barrier
